# v30 plus all per-segment s_setprio removed from the GEMM K-loops (age-based arbitration)
# baseline (speedup 1.0000x reference)
.LBB0_116:
	ds_read_b128 v[128:131], v229
	ds_read_b128 v[132:135], v229 offset:1024
	ds_read_b128 v[136:139], v229 offset:2048
	ds_read_b128 v[140:143], v229 offset:3072
	ds_read_b128 v[144:147], v230
	ds_read_b128 v[148:151], v230 offset:1024
	ds_read_b128 v[152:155], v230 offset:2048
	ds_read_b128 v[156:159], v230 offset:3072
	s_add_u32 vcc_lo, s94, 0x100
	s_addc_u32 vcc_hi, s95, 0
	s_cmp_eq_u32 s37, 60
	s_cselect_b32 s53, s89, vcc_hi
	s_cselect_b32 s52, s93, vcc_lo
	s_cselect_b32 s97, s85, s36
	s_cselect_b32 s96, s34, s35
	v_lshl_add_u64 v[210:211], s[94:95], 0, v[178:179]
	s_add_i32 m0, s67, 0xc000
	ds_read_b128 v[160:163], v231
	ds_read_b128 v[164:167], v231 offset:1024
	ds_read_b128 v[186:189], v231 offset:2048
	ds_read_b128 v[190:193], v231 offset:3072
	ds_read_b128 v[194:197], v231 offset:4096
	ds_read_b128 v[198:201], v231 offset:5120
	ds_read_b128 v[202:205], v231 offset:6144
	ds_read_b128 v[206:209], v231 offset:7168
	global_load_lds_dwordx4 v[210:211], off
	v_lshl_add_u64 v[210:211], s[94:95], 0, v[180:181]
	s_add_i32 m0, s67, 0xe000
	s_nop 0
	global_load_lds_dwordx4 v[210:211], off
	s_waitcnt vmcnt(8)
	s_waitcnt lgkmcnt(0)
	s_barrier
	s_waitcnt lgkmcnt(0)
	v_mfma_f32_16x16x32_bf16 v[124:127], v[128:131], v[160:163], v[124:127]
	v_mfma_f32_16x16x32_bf16 v[120:123], v[136:139], v[160:163], v[120:123]
	v_mfma_f32_16x16x32_bf16 v[112:115], v[128:131], v[186:189], v[112:115]
	v_mfma_f32_16x16x32_bf16 v[104:107], v[136:139], v[186:189], v[104:107]
	v_mfma_f32_16x16x32_bf16 v[96:99], v[128:131], v[194:197], v[96:99]
	v_mfma_f32_16x16x32_bf16 v[88:91], v[136:139], v[194:197], v[88:91]
	v_mfma_f32_16x16x32_bf16 v[80:83], v[128:131], v[202:205], v[80:83]
	v_mfma_f32_16x16x32_bf16 v[72:75], v[136:139], v[202:205], v[72:75]
	v_mfma_f32_16x16x32_bf16 v[124:127], v[132:135], v[164:167], v[124:127]
	v_mfma_f32_16x16x32_bf16 v[120:123], v[140:143], v[164:167], v[120:123]
	v_mfma_f32_16x16x32_bf16 v[112:115], v[132:135], v[190:193], v[112:115]
	v_mfma_f32_16x16x32_bf16 v[104:107], v[140:143], v[190:193], v[104:107]
	v_mfma_f32_16x16x32_bf16 v[96:99], v[132:135], v[198:201], v[96:99]
	v_mfma_f32_16x16x32_bf16 v[88:91], v[140:143], v[198:201], v[88:91]
	v_mfma_f32_16x16x32_bf16 v[80:83], v[132:135], v[206:209], v[80:83]
	v_mfma_f32_16x16x32_bf16 v[72:75], v[140:143], v[206:209], v[72:75]
	v_mfma_f32_16x16x32_bf16 v[116:119], v[144:147], v[160:163], v[116:119]
	v_mfma_f32_16x16x32_bf16 v[108:111], v[152:155], v[160:163], v[108:111]
	v_mfma_f32_16x16x32_bf16 v[100:103], v[144:147], v[186:189], v[100:103]
	v_mfma_f32_16x16x32_bf16 v[92:95], v[152:155], v[186:189], v[92:95]
	v_mfma_f32_16x16x32_bf16 v[84:87], v[144:147], v[194:197], v[84:87]
	v_mfma_f32_16x16x32_bf16 v[76:79], v[152:155], v[194:197], v[76:79]
	v_mfma_f32_16x16x32_bf16 v[68:71], v[144:147], v[202:205], v[68:71]
	v_mfma_f32_16x16x32_bf16 v[64:67], v[152:155], v[202:205], v[64:67]
	v_mfma_f32_16x16x32_bf16 v[116:119], v[148:151], v[164:167], v[116:119]
	v_mfma_f32_16x16x32_bf16 v[108:111], v[156:159], v[164:167], v[108:111]
	v_mfma_f32_16x16x32_bf16 v[100:103], v[148:151], v[190:193], v[100:103]
	v_mfma_f32_16x16x32_bf16 v[92:95], v[156:159], v[190:193], v[92:95]
	v_mfma_f32_16x16x32_bf16 v[84:87], v[148:151], v[198:201], v[84:87]
	v_mfma_f32_16x16x32_bf16 v[76:79], v[156:159], v[198:201], v[76:79]
	v_mfma_f32_16x16x32_bf16 v[68:71], v[148:151], v[206:209], v[68:71]
	v_mfma_f32_16x16x32_bf16 v[64:67], v[156:159], v[206:209], v[64:67]
	s_barrier
	s_add_i32 s38, s81, s91
	v_lshl_add_u64 v[210:211], s[96:97], 0, v[170:171]
	s_mov_b32 m0, s38
	ds_read_b128 v[160:163], v231 offset:16384
	ds_read_b128 v[164:167], v231 offset:17408
	ds_read_b128 v[186:189], v231 offset:18432
	ds_read_b128 v[190:193], v231 offset:19456
	ds_read_b128 v[194:197], v231 offset:20480
	ds_read_b128 v[198:201], v231 offset:21504
	ds_read_b128 v[202:205], v231 offset:22528
	ds_read_b128 v[206:209], v231 offset:23552
	global_load_lds_dwordx4 v[210:211], off
	s_add_i32 m0, s38, 0x2000
	s_add_u32 s38, s96, 0x100000
	v_lshl_add_u64 v[212:213], s[96:97], 0, v[174:175]
	s_addc_u32 s39, s97, 0
	s_add_i32 s40, s14, s91
	global_load_lds_dwordx4 v[212:213], off
	v_lshl_add_u64 v[214:215], s[38:39], 0, v[170:171]
	s_mov_b32 m0, s40
	v_lshl_add_u64 v[216:217], s[52:53], 0, v[172:173]
	global_load_lds_dwordx4 v[214:215], off
	v_lshl_add_u64 v[214:215], s[38:39], 0, v[174:175]
	s_add_i32 m0, s40, 0x2000
	s_nop 0
	global_load_lds_dwordx4 v[214:215], off
	v_lshl_add_u64 v[214:215], s[52:53], 0, v[168:169]
	s_mov_b32 m0, s67
	s_nop 0
	global_load_lds_dwordx4 v[214:215], off
	s_mov_b32 m0, s16
	s_nop 0
	global_load_lds_dwordx4 v[216:217], off
	s_waitcnt vmcnt(8)
	s_waitcnt lgkmcnt(0)
	s_barrier
	s_waitcnt lgkmcnt(0)
	v_mfma_f32_16x16x32_bf16 v[60:63], v[128:131], v[160:163], v[60:63]
	v_mfma_f32_16x16x32_bf16 v[56:59], v[136:139], v[160:163], v[56:59]
	v_mfma_f32_16x16x32_bf16 v[44:47], v[128:131], v[186:189], v[44:47]
	v_mfma_f32_16x16x32_bf16 v[40:43], v[136:139], v[186:189], v[40:43]
	v_mfma_f32_16x16x32_bf16 v[28:31], v[128:131], v[194:197], v[28:31]
	v_mfma_f32_16x16x32_bf16 v[24:27], v[136:139], v[194:197], v[24:27]
	v_mfma_f32_16x16x32_bf16 v[12:15], v[128:131], v[202:205], v[12:15]
	v_mfma_f32_16x16x32_bf16 v[8:11], v[136:139], v[202:205], v[8:11]
	v_mfma_f32_16x16x32_bf16 v[60:63], v[132:135], v[164:167], v[60:63]
	v_mfma_f32_16x16x32_bf16 v[56:59], v[140:143], v[164:167], v[56:59]
	v_mfma_f32_16x16x32_bf16 v[44:47], v[132:135], v[190:193], v[44:47]
	v_mfma_f32_16x16x32_bf16 v[40:43], v[140:143], v[190:193], v[40:43]
	v_mfma_f32_16x16x32_bf16 v[28:31], v[132:135], v[198:201], v[28:31]
	v_mfma_f32_16x16x32_bf16 v[24:27], v[140:143], v[198:201], v[24:27]
	v_mfma_f32_16x16x32_bf16 v[12:15], v[132:135], v[206:209], v[12:15]
	v_mfma_f32_16x16x32_bf16 v[8:11], v[140:143], v[206:209], v[8:11]
	v_mfma_f32_16x16x32_bf16 v[52:55], v[144:147], v[160:163], v[52:55]
	v_mfma_f32_16x16x32_bf16 v[48:51], v[152:155], v[160:163], v[48:51]
	v_mfma_f32_16x16x32_bf16 v[36:39], v[144:147], v[186:189], v[36:39]
	v_mfma_f32_16x16x32_bf16 v[32:35], v[152:155], v[186:189], v[32:35]
	v_mfma_f32_16x16x32_bf16 v[20:23], v[144:147], v[194:197], v[20:23]
	v_mfma_f32_16x16x32_bf16 v[16:19], v[152:155], v[194:197], v[16:19]
	v_mfma_f32_16x16x32_bf16 v[4:7], v[144:147], v[202:205], v[4:7]
	v_mfma_f32_16x16x32_bf16 v[0:3], v[152:155], v[202:205], v[0:3]
	v_mfma_f32_16x16x32_bf16 v[52:55], v[148:151], v[164:167], v[52:55]
	v_mfma_f32_16x16x32_bf16 v[48:51], v[156:159], v[164:167], v[48:51]
	v_mfma_f32_16x16x32_bf16 v[36:39], v[148:151], v[190:193], v[36:39]
	v_mfma_f32_16x16x32_bf16 v[32:35], v[156:159], v[190:193], v[32:35]
	v_mfma_f32_16x16x32_bf16 v[20:23], v[148:151], v[198:201], v[20:23]
	v_mfma_f32_16x16x32_bf16 v[16:19], v[156:159], v[198:201], v[16:19]
	v_mfma_f32_16x16x32_bf16 v[4:7], v[148:151], v[206:209], v[4:7]
	v_mfma_f32_16x16x32_bf16 v[0:3], v[156:159], v[206:209], v[0:3]
	s_barrier
	s_add_i32 s40, 0, 0x18000
	s_add_i32 s41, 0, 0x1c000
	v_add_u32_e32 v140, s40, v225
	v_add_u32_e32 v156, s41, v225
	ds_read_b128 v[128:131], v140
	ds_read_b128 v[132:135], v140 offset:1024
	ds_read_b128 v[136:139], v140 offset:2048
	ds_read_b128 v[140:143], v140 offset:3072
	ds_read_b128 v[144:147], v156
	ds_read_b128 v[148:151], v156 offset:1024
	ds_read_b128 v[152:155], v156 offset:2048
	ds_read_b128 v[156:159], v156 offset:3072
	s_add_u32 s38, s52, 0x100000
	s_addc_u32 s39, s53, 0
	s_mov_b32 m0, s17
	v_lshl_add_u64 v[218:219], s[38:39], 0, v[168:169]
	ds_read_b128 v[160:163], v231 offset:32768
	ds_read_b128 v[164:167], v231 offset:33792
	ds_read_b128 v[186:189], v231 offset:34816
	ds_read_b128 v[190:193], v231 offset:35840
	ds_read_b128 v[194:197], v231 offset:36864
	ds_read_b128 v[198:201], v231 offset:37888
	ds_read_b128 v[202:205], v231 offset:38912
	ds_read_b128 v[206:209], v231 offset:39936
	global_load_lds_dwordx4 v[218:219], off
	v_lshl_add_u64 v[218:219], s[38:39], 0, v[172:173]
	s_mov_b32 m0, s10
	s_nop 0
	global_load_lds_dwordx4 v[218:219], off
	s_waitcnt vmcnt(8)
	s_waitcnt lgkmcnt(0)
	s_barrier
	s_waitcnt lgkmcnt(0)
	v_mfma_f32_16x16x32_bf16 v[124:127], v[128:131], v[160:163], v[124:127]
	v_mfma_f32_16x16x32_bf16 v[120:123], v[136:139], v[160:163], v[120:123]
	v_mfma_f32_16x16x32_bf16 v[112:115], v[128:131], v[186:189], v[112:115]
	v_mfma_f32_16x16x32_bf16 v[104:107], v[136:139], v[186:189], v[104:107]
	v_mfma_f32_16x16x32_bf16 v[96:99], v[128:131], v[194:197], v[96:99]
	v_mfma_f32_16x16x32_bf16 v[88:91], v[136:139], v[194:197], v[88:91]
	v_mfma_f32_16x16x32_bf16 v[80:83], v[128:131], v[202:205], v[80:83]
	v_mfma_f32_16x16x32_bf16 v[72:75], v[136:139], v[202:205], v[72:75]
	v_mfma_f32_16x16x32_bf16 v[124:127], v[132:135], v[164:167], v[124:127]
	v_mfma_f32_16x16x32_bf16 v[120:123], v[140:143], v[164:167], v[120:123]
	v_mfma_f32_16x16x32_bf16 v[112:115], v[132:135], v[190:193], v[112:115]
	v_mfma_f32_16x16x32_bf16 v[104:107], v[140:143], v[190:193], v[104:107]
	v_mfma_f32_16x16x32_bf16 v[96:99], v[132:135], v[198:201], v[96:99]
	v_mfma_f32_16x16x32_bf16 v[88:91], v[140:143], v[198:201], v[88:91]
	v_mfma_f32_16x16x32_bf16 v[80:83], v[132:135], v[206:209], v[80:83]
	v_mfma_f32_16x16x32_bf16 v[72:75], v[140:143], v[206:209], v[72:75]
	v_mfma_f32_16x16x32_bf16 v[116:119], v[144:147], v[160:163], v[116:119]
	v_mfma_f32_16x16x32_bf16 v[108:111], v[152:155], v[160:163], v[108:111]
	v_mfma_f32_16x16x32_bf16 v[100:103], v[144:147], v[186:189], v[100:103]
	v_mfma_f32_16x16x32_bf16 v[92:95], v[152:155], v[186:189], v[92:95]
	v_mfma_f32_16x16x32_bf16 v[84:87], v[144:147], v[194:197], v[84:87]
	v_mfma_f32_16x16x32_bf16 v[76:79], v[152:155], v[194:197], v[76:79]
	v_mfma_f32_16x16x32_bf16 v[68:71], v[144:147], v[202:205], v[68:71]
	v_mfma_f32_16x16x32_bf16 v[64:67], v[152:155], v[202:205], v[64:67]
	v_mfma_f32_16x16x32_bf16 v[116:119], v[148:151], v[164:167], v[116:119]
	v_mfma_f32_16x16x32_bf16 v[108:111], v[156:159], v[164:167], v[108:111]
	v_mfma_f32_16x16x32_bf16 v[100:103], v[148:151], v[190:193], v[100:103]
	v_mfma_f32_16x16x32_bf16 v[92:95], v[156:159], v[190:193], v[92:95]
	v_mfma_f32_16x16x32_bf16 v[84:87], v[148:151], v[198:201], v[84:87]
	v_mfma_f32_16x16x32_bf16 v[76:79], v[156:159], v[198:201], v[76:79]
	v_mfma_f32_16x16x32_bf16 v[68:71], v[148:151], v[206:209], v[68:71]
	v_mfma_f32_16x16x32_bf16 v[64:67], v[156:159], v[206:209], v[64:67]
	s_barrier
	s_add_i32 s38, s40, s91
	v_lshl_add_u64 v[210:211], v[210:211], 0, s[56:57]
	s_mov_b32 m0, s38
	ds_read_b128 v[160:163], v231 offset:49152
	ds_read_b128 v[164:167], v231 offset:50176
	ds_read_b128 v[186:189], v231 offset:51200
	ds_read_b128 v[190:193], v231 offset:52224
	ds_read_b128 v[194:197], v231 offset:53248
	ds_read_b128 v[198:201], v231 offset:54272
	ds_read_b128 v[202:205], v231 offset:55296
	ds_read_b128 v[206:209], v231 offset:56320
	global_load_lds_dwordx4 v[210:211], off
	s_add_i32 m0, s38, 0x2000
	s_add_u32 s38, s96, 0x100080
	v_lshl_add_u64 v[210:211], v[212:213], 0, s[56:57]
	s_addc_u32 s39, s97, 0
	s_add_i32 s40, s41, s91
	global_load_lds_dwordx4 v[210:211], off
	v_lshl_add_u64 v[210:211], s[38:39], 0, v[170:171]
	s_mov_b32 m0, s40
	s_nop 0
	global_load_lds_dwordx4 v[210:211], off
	v_lshl_add_u64 v[210:211], s[38:39], 0, v[174:175]
	s_add_i32 m0, s40, 0x2000
	s_nop 0
	global_load_lds_dwordx4 v[210:211], off
	v_lshl_add_u64 v[210:211], v[214:215], 0, s[56:57]
	s_mov_b32 m0, s13
	s_nop 0
	global_load_lds_dwordx4 v[210:211], off
	v_lshl_add_u64 v[210:211], v[216:217], 0, s[56:57]
	s_mov_b32 m0, s77
	s_nop 0
	global_load_lds_dwordx4 v[210:211], off
	s_waitcnt vmcnt(8)
	s_waitcnt lgkmcnt(0)
	s_barrier
	s_waitcnt lgkmcnt(0)
	v_mfma_f32_16x16x32_bf16 v[60:63], v[128:131], v[160:163], v[60:63]
	v_mfma_f32_16x16x32_bf16 v[56:59], v[136:139], v[160:163], v[56:59]
	v_mfma_f32_16x16x32_bf16 v[44:47], v[128:131], v[186:189], v[44:47]
	v_mfma_f32_16x16x32_bf16 v[40:43], v[136:139], v[186:189], v[40:43]
	v_mfma_f32_16x16x32_bf16 v[28:31], v[128:131], v[194:197], v[28:31]
	v_mfma_f32_16x16x32_bf16 v[24:27], v[136:139], v[194:197], v[24:27]
	v_mfma_f32_16x16x32_bf16 v[12:15], v[128:131], v[202:205], v[12:15]
	v_mfma_f32_16x16x32_bf16 v[8:11], v[136:139], v[202:205], v[8:11]
	v_mfma_f32_16x16x32_bf16 v[60:63], v[132:135], v[164:167], v[60:63]
	v_mfma_f32_16x16x32_bf16 v[56:59], v[140:143], v[164:167], v[56:59]
	v_mfma_f32_16x16x32_bf16 v[44:47], v[132:135], v[190:193], v[44:47]
	v_mfma_f32_16x16x32_bf16 v[40:43], v[140:143], v[190:193], v[40:43]
	v_mfma_f32_16x16x32_bf16 v[28:31], v[132:135], v[198:201], v[28:31]
	v_mfma_f32_16x16x32_bf16 v[24:27], v[140:143], v[198:201], v[24:27]
	v_mfma_f32_16x16x32_bf16 v[12:15], v[132:135], v[206:209], v[12:15]
	v_mfma_f32_16x16x32_bf16 v[8:11], v[140:143], v[206:209], v[8:11]
	v_mfma_f32_16x16x32_bf16 v[52:55], v[144:147], v[160:163], v[52:55]
	v_mfma_f32_16x16x32_bf16 v[48:51], v[152:155], v[160:163], v[48:51]
	v_mfma_f32_16x16x32_bf16 v[36:39], v[144:147], v[186:189], v[36:39]
	v_mfma_f32_16x16x32_bf16 v[32:35], v[152:155], v[186:189], v[32:35]
	v_mfma_f32_16x16x32_bf16 v[20:23], v[144:147], v[194:197], v[20:23]
	v_mfma_f32_16x16x32_bf16 v[16:19], v[152:155], v[194:197], v[16:19]
	v_mfma_f32_16x16x32_bf16 v[4:7], v[144:147], v[202:205], v[4:7]
	v_mfma_f32_16x16x32_bf16 v[0:3], v[152:155], v[202:205], v[0:3]
	v_mfma_f32_16x16x32_bf16 v[52:55], v[148:151], v[164:167], v[52:55]
	v_mfma_f32_16x16x32_bf16 v[48:51], v[156:159], v[164:167], v[48:51]
	v_mfma_f32_16x16x32_bf16 v[36:39], v[148:151], v[190:193], v[36:39]
	v_mfma_f32_16x16x32_bf16 v[32:35], v[156:159], v[190:193], v[32:35]
	v_mfma_f32_16x16x32_bf16 v[20:23], v[148:151], v[198:201], v[20:23]
	v_mfma_f32_16x16x32_bf16 v[16:19], v[156:159], v[198:201], v[16:19]
	v_mfma_f32_16x16x32_bf16 v[4:7], v[148:151], v[206:209], v[4:7]
	v_mfma_f32_16x16x32_bf16 v[0:3], v[156:159], v[206:209], v[0:3]
	s_barrier
	s_add_i32 s37, s37, 2
	s_add_u32 s35, s35, 0x100
	s_addc_u32 s36, s36, 0
	s_cmp_gt_u32 s37, 61
	s_mov_b64 s[94:95], vcc
	s_cbranch_scc0 .LBB0_116
	s_and_b64 vcc, exec, s[64:65]
	s_cbranch_vccz .LBB0_119
	s_barrier

.LBB0_521:
	ds_read_b128 v[152:155], v149
	ds_read_b128 v[156:159], v149 offset:1024
	ds_read_b128 v[160:163], v149 offset:2048
	ds_read_b128 v[164:167], v149 offset:3072
	ds_read_b128 v[168:171], v150
	ds_read_b128 v[172:175], v150 offset:1024
	ds_read_b128 v[176:179], v150 offset:2048
	ds_read_b128 v[180:183], v150 offset:3072
	s_add_u32 s37, s46, 0xfff80080
	s_addc_u32 s38, s47, -1
	s_cmp_eq_u32 s36, 28
	s_cselect_b32 s51, s13, s38
	s_cselect_b32 s50, s64, s37
	s_cselect_b32 s49, s11, s35
	s_cselect_b32 s48, s65, s34
	v_lshl_add_u64 v[144:145], s[46:47], 0, v[136:137]
	s_add_i32 m0, s17, 0xc000
	ds_read_b128 v[184:187], v151
	ds_read_b128 v[188:191], v151 offset:1024
	ds_read_b128 v[192:195], v151 offset:2048
	ds_read_b128 v[196:199], v151 offset:3072
	ds_read_b128 v[200:203], v151 offset:4096
	ds_read_b128 v[204:207], v151 offset:5120
	ds_read_b128 v[208:211], v151 offset:6144
	ds_read_b128 v[212:215], v151 offset:7168
	global_load_lds_dwordx4 v[144:145], off
	v_lshl_add_u64 v[144:145], s[46:47], 0, v[138:139]
	s_add_i32 m0, s17, 0xe000
	s_nop 0
	global_load_lds_dwordx4 v[144:145], off
	s_waitcnt vmcnt(8)
	s_waitcnt lgkmcnt(0)
	s_barrier
	s_waitcnt lgkmcnt(0)
	v_mfma_f32_16x16x32_bf16 v[124:127], v[152:155], v[184:187], v[124:127]
	v_mfma_f32_16x16x32_bf16 v[120:123], v[160:163], v[184:187], v[120:123]
	v_mfma_f32_16x16x32_bf16 v[116:119], v[152:155], v[192:195], v[116:119]
	v_mfma_f32_16x16x32_bf16 v[108:111], v[160:163], v[192:195], v[108:111]
	v_mfma_f32_16x16x32_bf16 v[100:103], v[152:155], v[200:203], v[100:103]
	v_mfma_f32_16x16x32_bf16 v[92:95], v[160:163], v[200:203], v[92:95]
	v_mfma_f32_16x16x32_bf16 v[84:87], v[152:155], v[208:211], v[84:87]
	v_mfma_f32_16x16x32_bf16 v[76:79], v[160:163], v[208:211], v[76:79]
	v_mfma_f32_16x16x32_bf16 v[124:127], v[156:159], v[188:191], v[124:127]
	v_mfma_f32_16x16x32_bf16 v[120:123], v[164:167], v[188:191], v[120:123]
	v_mfma_f32_16x16x32_bf16 v[116:119], v[156:159], v[196:199], v[116:119]
	v_mfma_f32_16x16x32_bf16 v[108:111], v[164:167], v[196:199], v[108:111]
	v_mfma_f32_16x16x32_bf16 v[100:103], v[156:159], v[204:207], v[100:103]
	v_mfma_f32_16x16x32_bf16 v[92:95], v[164:167], v[204:207], v[92:95]
	v_mfma_f32_16x16x32_bf16 v[84:87], v[156:159], v[212:215], v[84:87]
	v_mfma_f32_16x16x32_bf16 v[76:79], v[164:167], v[212:215], v[76:79]
	v_mfma_f32_16x16x32_bf16 v[112:115], v[168:171], v[184:187], v[112:115]
	v_mfma_f32_16x16x32_bf16 v[104:107], v[176:179], v[184:187], v[104:107]
	v_mfma_f32_16x16x32_bf16 v[96:99], v[168:171], v[192:195], v[96:99]
	v_mfma_f32_16x16x32_bf16 v[88:91], v[176:179], v[192:195], v[88:91]
	v_mfma_f32_16x16x32_bf16 v[80:83], v[168:171], v[200:203], v[80:83]
	v_mfma_f32_16x16x32_bf16 v[72:75], v[176:179], v[200:203], v[72:75]
	v_mfma_f32_16x16x32_bf16 v[68:71], v[168:171], v[208:211], v[68:71]
	v_mfma_f32_16x16x32_bf16 v[64:67], v[176:179], v[208:211], v[64:67]
	v_mfma_f32_16x16x32_bf16 v[112:115], v[172:175], v[188:191], v[112:115]
	v_mfma_f32_16x16x32_bf16 v[104:107], v[180:183], v[188:191], v[104:107]
	v_mfma_f32_16x16x32_bf16 v[96:99], v[172:175], v[196:199], v[96:99]
	v_mfma_f32_16x16x32_bf16 v[88:91], v[180:183], v[196:199], v[88:91]
	v_mfma_f32_16x16x32_bf16 v[80:83], v[172:175], v[204:207], v[80:83]
	v_mfma_f32_16x16x32_bf16 v[72:75], v[180:183], v[204:207], v[72:75]
	v_mfma_f32_16x16x32_bf16 v[68:71], v[172:175], v[212:215], v[68:71]
	v_mfma_f32_16x16x32_bf16 v[64:67], v[180:183], v[212:215], v[64:67]
	s_barrier
	s_add_i32 s37, s61, s53
	v_lshl_add_u64 v[144:145], s[48:49], 0, v[130:131]
	s_mov_b32 m0, s37
	ds_read_b128 v[184:187], v151 offset:16384
	ds_read_b128 v[188:191], v151 offset:17408
	ds_read_b128 v[192:195], v151 offset:18432
	ds_read_b128 v[196:199], v151 offset:19456
	ds_read_b128 v[200:203], v151 offset:20480
	ds_read_b128 v[204:207], v151 offset:21504
	ds_read_b128 v[208:211], v151 offset:22528
	ds_read_b128 v[212:215], v151 offset:23552
	global_load_lds_dwordx4 v[144:145], off
	s_add_i32 m0, s37, 0x2000
	s_add_u32 s38, s48, 0x80000
	v_lshl_add_u64 v[216:217], s[48:49], 0, v[134:135]
	s_addc_u32 s39, s49, 0
	s_add_i32 s37, s62, s53
	global_load_lds_dwordx4 v[216:217], off
	v_lshl_add_u64 v[218:219], s[38:39], 0, v[130:131]
	s_mov_b32 m0, s37
	v_lshl_add_u64 v[220:221], s[50:51], 0, v[132:133]
	global_load_lds_dwordx4 v[218:219], off
	v_lshl_add_u64 v[218:219], s[38:39], 0, v[134:135]
	s_add_i32 m0, s37, 0x2000
	s_nop 0
	global_load_lds_dwordx4 v[218:219], off
	v_lshl_add_u64 v[218:219], s[50:51], 0, v[128:129]
	s_mov_b32 m0, s17
	s_nop 0
	global_load_lds_dwordx4 v[218:219], off
	s_mov_b32 m0, s54
	s_nop 0
	global_load_lds_dwordx4 v[220:221], off
	s_waitcnt vmcnt(8)
	s_waitcnt lgkmcnt(0)
	s_barrier
	s_waitcnt lgkmcnt(0)
	v_mfma_f32_16x16x32_bf16 v[60:63], v[152:155], v[184:187], v[60:63]
	v_mfma_f32_16x16x32_bf16 v[56:59], v[160:163], v[184:187], v[56:59]
	v_mfma_f32_16x16x32_bf16 v[52:55], v[152:155], v[192:195], v[52:55]
	v_mfma_f32_16x16x32_bf16 v[44:47], v[160:163], v[192:195], v[44:47]
	v_mfma_f32_16x16x32_bf16 v[36:39], v[152:155], v[200:203], v[36:39]
	v_mfma_f32_16x16x32_bf16 v[28:31], v[160:163], v[200:203], v[28:31]
	v_mfma_f32_16x16x32_bf16 v[20:23], v[152:155], v[208:211], v[20:23]
	v_mfma_f32_16x16x32_bf16 v[12:15], v[160:163], v[208:211], v[12:15]
	v_mfma_f32_16x16x32_bf16 v[60:63], v[156:159], v[188:191], v[60:63]
	v_mfma_f32_16x16x32_bf16 v[56:59], v[164:167], v[188:191], v[56:59]
	v_mfma_f32_16x16x32_bf16 v[52:55], v[156:159], v[196:199], v[52:55]
	v_mfma_f32_16x16x32_bf16 v[44:47], v[164:167], v[196:199], v[44:47]
	v_mfma_f32_16x16x32_bf16 v[36:39], v[156:159], v[204:207], v[36:39]
	v_mfma_f32_16x16x32_bf16 v[28:31], v[164:167], v[204:207], v[28:31]
	v_mfma_f32_16x16x32_bf16 v[20:23], v[156:159], v[212:215], v[20:23]
	v_mfma_f32_16x16x32_bf16 v[12:15], v[164:167], v[212:215], v[12:15]
	v_mfma_f32_16x16x32_bf16 v[48:51], v[168:171], v[184:187], v[48:51]
	v_mfma_f32_16x16x32_bf16 v[40:43], v[176:179], v[184:187], v[40:43]
	v_mfma_f32_16x16x32_bf16 v[32:35], v[168:171], v[192:195], v[32:35]
	v_mfma_f32_16x16x32_bf16 v[24:27], v[176:179], v[192:195], v[24:27]
	v_mfma_f32_16x16x32_bf16 v[16:19], v[168:171], v[200:203], v[16:19]
	v_mfma_f32_16x16x32_bf16 v[8:11], v[176:179], v[200:203], v[8:11]
	v_mfma_f32_16x16x32_bf16 v[4:7], v[168:171], v[208:211], v[4:7]
	v_mfma_f32_16x16x32_bf16 v[0:3], v[176:179], v[208:211], v[0:3]
	v_mfma_f32_16x16x32_bf16 v[48:51], v[172:175], v[188:191], v[48:51]
	v_mfma_f32_16x16x32_bf16 v[40:43], v[180:183], v[188:191], v[40:43]
	v_mfma_f32_16x16x32_bf16 v[32:35], v[172:175], v[196:199], v[32:35]
	v_mfma_f32_16x16x32_bf16 v[24:27], v[180:183], v[196:199], v[24:27]
	v_mfma_f32_16x16x32_bf16 v[16:19], v[172:175], v[204:207], v[16:19]
	v_mfma_f32_16x16x32_bf16 v[8:11], v[180:183], v[204:207], v[8:11]
	v_mfma_f32_16x16x32_bf16 v[4:7], v[172:175], v[212:215], v[4:7]
	v_mfma_f32_16x16x32_bf16 v[0:3], v[180:183], v[212:215], v[0:3]
	s_barrier
	s_add_i32 s37, 0, 0x18000
	s_add_i32 s40, 0, 0x1c000
	v_add_u32_e32 v164, s37, v147
	v_add_u32_e32 v180, s40, v147
	ds_read_b128 v[152:155], v164
	ds_read_b128 v[156:159], v164 offset:1024
	ds_read_b128 v[160:163], v164 offset:2048
	ds_read_b128 v[164:167], v164 offset:3072
	ds_read_b128 v[168:171], v180
	ds_read_b128 v[172:175], v180 offset:1024
	ds_read_b128 v[176:179], v180 offset:2048
	ds_read_b128 v[180:183], v180 offset:3072
	s_add_u32 s38, s50, 0x80000
	s_addc_u32 s39, s51, 0
	s_mov_b32 m0, s55
	v_lshl_add_u64 v[222:223], s[38:39], 0, v[128:129]
	ds_read_b128 v[184:187], v151 offset:32768
	ds_read_b128 v[188:191], v151 offset:33792
	ds_read_b128 v[192:195], v151 offset:34816
	ds_read_b128 v[196:199], v151 offset:35840
	ds_read_b128 v[200:203], v151 offset:36864
	ds_read_b128 v[204:207], v151 offset:37888
	ds_read_b128 v[208:211], v151 offset:38912
	ds_read_b128 v[212:215], v151 offset:39936
	global_load_lds_dwordx4 v[222:223], off
	v_lshl_add_u64 v[222:223], s[38:39], 0, v[132:133]
	s_mov_b32 m0, s56
	s_nop 0
	global_load_lds_dwordx4 v[222:223], off
	s_waitcnt vmcnt(8)
	s_waitcnt lgkmcnt(0)
	s_barrier
	s_waitcnt lgkmcnt(0)
	v_mfma_f32_16x16x32_bf16 v[124:127], v[152:155], v[184:187], v[124:127]
	v_mfma_f32_16x16x32_bf16 v[120:123], v[160:163], v[184:187], v[120:123]
	v_mfma_f32_16x16x32_bf16 v[116:119], v[152:155], v[192:195], v[116:119]
	v_mfma_f32_16x16x32_bf16 v[108:111], v[160:163], v[192:195], v[108:111]
	v_mfma_f32_16x16x32_bf16 v[100:103], v[152:155], v[200:203], v[100:103]
	v_mfma_f32_16x16x32_bf16 v[92:95], v[160:163], v[200:203], v[92:95]
	v_mfma_f32_16x16x32_bf16 v[84:87], v[152:155], v[208:211], v[84:87]
	v_mfma_f32_16x16x32_bf16 v[76:79], v[160:163], v[208:211], v[76:79]
	v_mfma_f32_16x16x32_bf16 v[124:127], v[156:159], v[188:191], v[124:127]
	v_mfma_f32_16x16x32_bf16 v[120:123], v[164:167], v[188:191], v[120:123]
	v_mfma_f32_16x16x32_bf16 v[116:119], v[156:159], v[196:199], v[116:119]
	v_mfma_f32_16x16x32_bf16 v[108:111], v[164:167], v[196:199], v[108:111]
	v_mfma_f32_16x16x32_bf16 v[100:103], v[156:159], v[204:207], v[100:103]
	v_mfma_f32_16x16x32_bf16 v[92:95], v[164:167], v[204:207], v[92:95]
	v_mfma_f32_16x16x32_bf16 v[84:87], v[156:159], v[212:215], v[84:87]
	v_mfma_f32_16x16x32_bf16 v[76:79], v[164:167], v[212:215], v[76:79]
	v_mfma_f32_16x16x32_bf16 v[112:115], v[168:171], v[184:187], v[112:115]
	v_mfma_f32_16x16x32_bf16 v[104:107], v[176:179], v[184:187], v[104:107]
	v_mfma_f32_16x16x32_bf16 v[96:99], v[168:171], v[192:195], v[96:99]
	v_mfma_f32_16x16x32_bf16 v[88:91], v[176:179], v[192:195], v[88:91]
	v_mfma_f32_16x16x32_bf16 v[80:83], v[168:171], v[200:203], v[80:83]
	v_mfma_f32_16x16x32_bf16 v[72:75], v[176:179], v[200:203], v[72:75]
	v_mfma_f32_16x16x32_bf16 v[68:71], v[168:171], v[208:211], v[68:71]
	v_mfma_f32_16x16x32_bf16 v[64:67], v[176:179], v[208:211], v[64:67]
	v_mfma_f32_16x16x32_bf16 v[112:115], v[172:175], v[188:191], v[112:115]
	v_mfma_f32_16x16x32_bf16 v[104:107], v[180:183], v[188:191], v[104:107]
	v_mfma_f32_16x16x32_bf16 v[96:99], v[172:175], v[196:199], v[96:99]
	v_mfma_f32_16x16x32_bf16 v[88:91], v[180:183], v[196:199], v[88:91]
	v_mfma_f32_16x16x32_bf16 v[80:83], v[172:175], v[204:207], v[80:83]
	v_mfma_f32_16x16x32_bf16 v[72:75], v[180:183], v[204:207], v[72:75]
	v_mfma_f32_16x16x32_bf16 v[68:71], v[172:175], v[212:215], v[68:71]
	v_mfma_f32_16x16x32_bf16 v[64:67], v[180:183], v[212:215], v[64:67]
	s_barrier
	s_add_i32 s37, s37, s53
	v_lshl_add_u64 v[144:145], v[144:145], 0, s[6:7]
	s_mov_b32 m0, s37
	ds_read_b128 v[184:187], v151 offset:49152
	ds_read_b128 v[188:191], v151 offset:50176
	ds_read_b128 v[192:195], v151 offset:51200
	ds_read_b128 v[196:199], v151 offset:52224
	ds_read_b128 v[200:203], v151 offset:53248
	ds_read_b128 v[204:207], v151 offset:54272
	ds_read_b128 v[208:211], v151 offset:55296
	ds_read_b128 v[212:215], v151 offset:56320
	global_load_lds_dwordx4 v[144:145], off
	s_add_i32 m0, s37, 0x2000
	s_add_u32 s38, s48, 0x80080
	v_lshl_add_u64 v[144:145], v[216:217], 0, s[6:7]
	s_addc_u32 s39, s49, 0
	s_add_i32 s37, s40, s53
	global_load_lds_dwordx4 v[144:145], off
	v_lshl_add_u64 v[144:145], s[38:39], 0, v[130:131]
	s_mov_b32 m0, s37
	s_nop 0
	global_load_lds_dwordx4 v[144:145], off
	v_lshl_add_u64 v[144:145], s[38:39], 0, v[134:135]
	s_add_i32 m0, s37, 0x2000
	s_nop 0
	global_load_lds_dwordx4 v[144:145], off
	v_lshl_add_u64 v[144:145], v[218:219], 0, s[6:7]
	s_mov_b32 m0, s58
	s_nop 0
	global_load_lds_dwordx4 v[144:145], off
	v_lshl_add_u64 v[144:145], v[220:221], 0, s[6:7]
	s_mov_b32 m0, s59
	s_nop 0
	global_load_lds_dwordx4 v[144:145], off
	s_waitcnt vmcnt(8)
	s_waitcnt lgkmcnt(0)
	s_barrier
	s_waitcnt lgkmcnt(0)
	v_mfma_f32_16x16x32_bf16 v[60:63], v[152:155], v[184:187], v[60:63]
	v_mfma_f32_16x16x32_bf16 v[56:59], v[160:163], v[184:187], v[56:59]
	v_mfma_f32_16x16x32_bf16 v[52:55], v[152:155], v[192:195], v[52:55]
	v_mfma_f32_16x16x32_bf16 v[44:47], v[160:163], v[192:195], v[44:47]
	v_mfma_f32_16x16x32_bf16 v[36:39], v[152:155], v[200:203], v[36:39]
	v_mfma_f32_16x16x32_bf16 v[28:31], v[160:163], v[200:203], v[28:31]
	v_mfma_f32_16x16x32_bf16 v[20:23], v[152:155], v[208:211], v[20:23]
	v_mfma_f32_16x16x32_bf16 v[12:15], v[160:163], v[208:211], v[12:15]
	v_mfma_f32_16x16x32_bf16 v[60:63], v[156:159], v[188:191], v[60:63]
	v_mfma_f32_16x16x32_bf16 v[56:59], v[164:167], v[188:191], v[56:59]
	v_mfma_f32_16x16x32_bf16 v[52:55], v[156:159], v[196:199], v[52:55]
	v_mfma_f32_16x16x32_bf16 v[44:47], v[164:167], v[196:199], v[44:47]
	v_mfma_f32_16x16x32_bf16 v[36:39], v[156:159], v[204:207], v[36:39]
	v_mfma_f32_16x16x32_bf16 v[28:31], v[164:167], v[204:207], v[28:31]
	v_mfma_f32_16x16x32_bf16 v[20:23], v[156:159], v[212:215], v[20:23]
	v_mfma_f32_16x16x32_bf16 v[12:15], v[164:167], v[212:215], v[12:15]
	v_mfma_f32_16x16x32_bf16 v[48:51], v[168:171], v[184:187], v[48:51]
	v_mfma_f32_16x16x32_bf16 v[40:43], v[176:179], v[184:187], v[40:43]
	v_mfma_f32_16x16x32_bf16 v[32:35], v[168:171], v[192:195], v[32:35]
	v_mfma_f32_16x16x32_bf16 v[24:27], v[176:179], v[192:195], v[24:27]
	v_mfma_f32_16x16x32_bf16 v[16:19], v[168:171], v[200:203], v[16:19]
	v_mfma_f32_16x16x32_bf16 v[8:11], v[176:179], v[200:203], v[8:11]
	v_mfma_f32_16x16x32_bf16 v[4:7], v[168:171], v[208:211], v[4:7]
	v_mfma_f32_16x16x32_bf16 v[0:3], v[176:179], v[208:211], v[0:3]
	v_mfma_f32_16x16x32_bf16 v[48:51], v[172:175], v[188:191], v[48:51]
	v_mfma_f32_16x16x32_bf16 v[40:43], v[180:183], v[188:191], v[40:43]
	v_mfma_f32_16x16x32_bf16 v[32:35], v[172:175], v[196:199], v[32:35]
	v_mfma_f32_16x16x32_bf16 v[24:27], v[180:183], v[196:199], v[24:27]
	v_mfma_f32_16x16x32_bf16 v[16:19], v[172:175], v[204:207], v[16:19]
	v_mfma_f32_16x16x32_bf16 v[8:11], v[180:183], v[204:207], v[8:11]
	v_mfma_f32_16x16x32_bf16 v[4:7], v[172:175], v[212:215], v[4:7]
	v_mfma_f32_16x16x32_bf16 v[0:3], v[180:183], v[212:215], v[0:3]
	s_barrier
	s_add_i32 s36, s36, 2
	s_add_u32 s46, s46, 0x100
	s_addc_u32 s47, s47, 0
	s_add_u32 s34, s34, 0x100
	s_addc_u32 s35, s35, 0
	s_cmp_gt_u32 s36, 29
	s_cbranch_scc0 .LBB0_521
	s_and_b64 vcc, exec, s[8:9]
	s_cbranch_vccz .LBB0_524
	s_barrier

.LBB0_600:
	ds_read_b128 v[152:155], v149
	ds_read_b128 v[156:159], v149 offset:1024
	ds_read_b128 v[160:163], v149 offset:2048
	ds_read_b128 v[164:167], v149 offset:3072
	ds_read_b128 v[168:171], v150
	ds_read_b128 v[172:175], v150 offset:1024
	ds_read_b128 v[176:179], v150 offset:2048
	ds_read_b128 v[180:183], v150 offset:3072
	s_add_u32 s37, s48, 0xfff00080
	s_addc_u32 s38, s49, -1
	s_cmp_eq_u32 s36, 60
	s_cselect_b32 s53, s17, s38
	s_cselect_b32 s52, s66, s37
	s_cselect_b32 s51, s13, s35
	s_cselect_b32 s50, s67, s34
	v_lshl_add_u64 v[144:145], s[48:49], 0, v[136:137]
	s_add_i32 m0, s19, 0xc000
	ds_read_b128 v[184:187], v151
	ds_read_b128 v[188:191], v151 offset:1024
	ds_read_b128 v[192:195], v151 offset:2048
	ds_read_b128 v[196:199], v151 offset:3072
	ds_read_b128 v[200:203], v151 offset:4096
	ds_read_b128 v[204:207], v151 offset:5120
	ds_read_b128 v[208:211], v151 offset:6144
	ds_read_b128 v[212:215], v151 offset:7168
	global_load_lds_dwordx4 v[144:145], off
	v_lshl_add_u64 v[144:145], s[48:49], 0, v[138:139]
	s_add_i32 m0, s19, 0xe000
	s_nop 0
	global_load_lds_dwordx4 v[144:145], off
	s_waitcnt vmcnt(8)
	s_waitcnt lgkmcnt(0)
	s_barrier
	s_waitcnt lgkmcnt(0)
	v_mfma_f32_16x16x32_bf16 v[124:127], v[152:155], v[184:187], v[124:127]
	v_mfma_f32_16x16x32_bf16 v[120:123], v[160:163], v[184:187], v[120:123]
	v_mfma_f32_16x16x32_bf16 v[116:119], v[152:155], v[192:195], v[116:119]
	v_mfma_f32_16x16x32_bf16 v[108:111], v[160:163], v[192:195], v[108:111]
	v_mfma_f32_16x16x32_bf16 v[100:103], v[152:155], v[200:203], v[100:103]
	v_mfma_f32_16x16x32_bf16 v[92:95], v[160:163], v[200:203], v[92:95]
	v_mfma_f32_16x16x32_bf16 v[84:87], v[152:155], v[208:211], v[84:87]
	v_mfma_f32_16x16x32_bf16 v[76:79], v[160:163], v[208:211], v[76:79]
	v_mfma_f32_16x16x32_bf16 v[124:127], v[156:159], v[188:191], v[124:127]
	v_mfma_f32_16x16x32_bf16 v[120:123], v[164:167], v[188:191], v[120:123]
	v_mfma_f32_16x16x32_bf16 v[116:119], v[156:159], v[196:199], v[116:119]
	v_mfma_f32_16x16x32_bf16 v[108:111], v[164:167], v[196:199], v[108:111]
	v_mfma_f32_16x16x32_bf16 v[100:103], v[156:159], v[204:207], v[100:103]
	v_mfma_f32_16x16x32_bf16 v[92:95], v[164:167], v[204:207], v[92:95]
	v_mfma_f32_16x16x32_bf16 v[84:87], v[156:159], v[212:215], v[84:87]
	v_mfma_f32_16x16x32_bf16 v[76:79], v[164:167], v[212:215], v[76:79]
	v_mfma_f32_16x16x32_bf16 v[112:115], v[168:171], v[184:187], v[112:115]
	v_mfma_f32_16x16x32_bf16 v[104:107], v[176:179], v[184:187], v[104:107]
	v_mfma_f32_16x16x32_bf16 v[96:99], v[168:171], v[192:195], v[96:99]
	v_mfma_f32_16x16x32_bf16 v[88:91], v[176:179], v[192:195], v[88:91]
	v_mfma_f32_16x16x32_bf16 v[80:83], v[168:171], v[200:203], v[80:83]
	v_mfma_f32_16x16x32_bf16 v[72:75], v[176:179], v[200:203], v[72:75]
	v_mfma_f32_16x16x32_bf16 v[68:71], v[168:171], v[208:211], v[68:71]
	v_mfma_f32_16x16x32_bf16 v[64:67], v[176:179], v[208:211], v[64:67]
	v_mfma_f32_16x16x32_bf16 v[112:115], v[172:175], v[188:191], v[112:115]
	v_mfma_f32_16x16x32_bf16 v[104:107], v[180:183], v[188:191], v[104:107]
	v_mfma_f32_16x16x32_bf16 v[96:99], v[172:175], v[196:199], v[96:99]
	v_mfma_f32_16x16x32_bf16 v[88:91], v[180:183], v[196:199], v[88:91]
	v_mfma_f32_16x16x32_bf16 v[80:83], v[172:175], v[204:207], v[80:83]
	v_mfma_f32_16x16x32_bf16 v[72:75], v[180:183], v[204:207], v[72:75]
	v_mfma_f32_16x16x32_bf16 v[68:71], v[172:175], v[212:215], v[68:71]
	v_mfma_f32_16x16x32_bf16 v[64:67], v[180:183], v[212:215], v[64:67]
	s_barrier
	s_add_i32 s37, s63, s55
	v_lshl_add_u64 v[144:145], s[50:51], 0, v[130:131]
	s_mov_b32 m0, s37
	ds_read_b128 v[184:187], v151 offset:16384
	ds_read_b128 v[188:191], v151 offset:17408
	ds_read_b128 v[192:195], v151 offset:18432
	ds_read_b128 v[196:199], v151 offset:19456
	ds_read_b128 v[200:203], v151 offset:20480
	ds_read_b128 v[204:207], v151 offset:21504
	ds_read_b128 v[208:211], v151 offset:22528
	ds_read_b128 v[212:215], v151 offset:23552
	global_load_lds_dwordx4 v[144:145], off
	s_add_i32 m0, s37, 0x2000
	s_add_u32 s38, s50, 0x100000
	v_lshl_add_u64 v[216:217], s[50:51], 0, v[134:135]
	s_addc_u32 s39, s51, 0
	s_add_i32 s37, s64, s55
	global_load_lds_dwordx4 v[216:217], off
	v_lshl_add_u64 v[218:219], s[38:39], 0, v[130:131]
	s_mov_b32 m0, s37
	v_lshl_add_u64 v[220:221], s[52:53], 0, v[132:133]
	global_load_lds_dwordx4 v[218:219], off
	v_lshl_add_u64 v[218:219], s[38:39], 0, v[134:135]
	s_add_i32 m0, s37, 0x2000
	s_nop 0
	global_load_lds_dwordx4 v[218:219], off
	v_lshl_add_u64 v[218:219], s[52:53], 0, v[128:129]
	s_mov_b32 m0, s19
	s_nop 0
	global_load_lds_dwordx4 v[218:219], off
	s_mov_b32 m0, s56
	s_nop 0
	global_load_lds_dwordx4 v[220:221], off
	s_waitcnt vmcnt(8)
	s_waitcnt lgkmcnt(0)
	s_barrier
	s_waitcnt lgkmcnt(0)
	v_mfma_f32_16x16x32_bf16 v[60:63], v[152:155], v[184:187], v[60:63]
	v_mfma_f32_16x16x32_bf16 v[56:59], v[160:163], v[184:187], v[56:59]
	v_mfma_f32_16x16x32_bf16 v[52:55], v[152:155], v[192:195], v[52:55]
	v_mfma_f32_16x16x32_bf16 v[44:47], v[160:163], v[192:195], v[44:47]
	v_mfma_f32_16x16x32_bf16 v[36:39], v[152:155], v[200:203], v[36:39]
	v_mfma_f32_16x16x32_bf16 v[28:31], v[160:163], v[200:203], v[28:31]
	v_mfma_f32_16x16x32_bf16 v[20:23], v[152:155], v[208:211], v[20:23]
	v_mfma_f32_16x16x32_bf16 v[12:15], v[160:163], v[208:211], v[12:15]
	v_mfma_f32_16x16x32_bf16 v[60:63], v[156:159], v[188:191], v[60:63]
	v_mfma_f32_16x16x32_bf16 v[56:59], v[164:167], v[188:191], v[56:59]
	v_mfma_f32_16x16x32_bf16 v[52:55], v[156:159], v[196:199], v[52:55]
	v_mfma_f32_16x16x32_bf16 v[44:47], v[164:167], v[196:199], v[44:47]
	v_mfma_f32_16x16x32_bf16 v[36:39], v[156:159], v[204:207], v[36:39]
	v_mfma_f32_16x16x32_bf16 v[28:31], v[164:167], v[204:207], v[28:31]
	v_mfma_f32_16x16x32_bf16 v[20:23], v[156:159], v[212:215], v[20:23]
	v_mfma_f32_16x16x32_bf16 v[12:15], v[164:167], v[212:215], v[12:15]
	v_mfma_f32_16x16x32_bf16 v[48:51], v[168:171], v[184:187], v[48:51]
	v_mfma_f32_16x16x32_bf16 v[40:43], v[176:179], v[184:187], v[40:43]
	v_mfma_f32_16x16x32_bf16 v[32:35], v[168:171], v[192:195], v[32:35]
	v_mfma_f32_16x16x32_bf16 v[24:27], v[176:179], v[192:195], v[24:27]
	v_mfma_f32_16x16x32_bf16 v[16:19], v[168:171], v[200:203], v[16:19]
	v_mfma_f32_16x16x32_bf16 v[8:11], v[176:179], v[200:203], v[8:11]
	v_mfma_f32_16x16x32_bf16 v[4:7], v[168:171], v[208:211], v[4:7]
	v_mfma_f32_16x16x32_bf16 v[0:3], v[176:179], v[208:211], v[0:3]
	v_mfma_f32_16x16x32_bf16 v[48:51], v[172:175], v[188:191], v[48:51]
	v_mfma_f32_16x16x32_bf16 v[40:43], v[180:183], v[188:191], v[40:43]
	v_mfma_f32_16x16x32_bf16 v[32:35], v[172:175], v[196:199], v[32:35]
	v_mfma_f32_16x16x32_bf16 v[24:27], v[180:183], v[196:199], v[24:27]
	v_mfma_f32_16x16x32_bf16 v[16:19], v[172:175], v[204:207], v[16:19]
	v_mfma_f32_16x16x32_bf16 v[8:11], v[180:183], v[204:207], v[8:11]
	v_mfma_f32_16x16x32_bf16 v[4:7], v[172:175], v[212:215], v[4:7]
	v_mfma_f32_16x16x32_bf16 v[0:3], v[180:183], v[212:215], v[0:3]
	s_barrier
	s_add_i32 s37, 0, 0x18000
	s_add_i32 s40, 0, 0x1c000
	v_add_u32_e32 v164, s37, v147
	v_add_u32_e32 v180, s40, v147
	ds_read_b128 v[152:155], v164
	ds_read_b128 v[156:159], v164 offset:1024
	ds_read_b128 v[160:163], v164 offset:2048
	ds_read_b128 v[164:167], v164 offset:3072
	ds_read_b128 v[168:171], v180
	ds_read_b128 v[172:175], v180 offset:1024
	ds_read_b128 v[176:179], v180 offset:2048
	ds_read_b128 v[180:183], v180 offset:3072
	s_add_u32 s38, s52, 0x100000
	s_addc_u32 s39, s53, 0
	s_mov_b32 m0, s57
	v_lshl_add_u64 v[222:223], s[38:39], 0, v[128:129]
	ds_read_b128 v[184:187], v151 offset:32768
	ds_read_b128 v[188:191], v151 offset:33792
	ds_read_b128 v[192:195], v151 offset:34816
	ds_read_b128 v[196:199], v151 offset:35840
	ds_read_b128 v[200:203], v151 offset:36864
	ds_read_b128 v[204:207], v151 offset:37888
	ds_read_b128 v[208:211], v151 offset:38912
	ds_read_b128 v[212:215], v151 offset:39936
	global_load_lds_dwordx4 v[222:223], off
	v_lshl_add_u64 v[222:223], s[38:39], 0, v[132:133]
	s_mov_b32 m0, s58
	s_nop 0
	global_load_lds_dwordx4 v[222:223], off
	s_waitcnt vmcnt(8)
	s_waitcnt lgkmcnt(0)
	s_barrier
	s_waitcnt lgkmcnt(0)
	v_mfma_f32_16x16x32_bf16 v[124:127], v[152:155], v[184:187], v[124:127]
	v_mfma_f32_16x16x32_bf16 v[120:123], v[160:163], v[184:187], v[120:123]
	v_mfma_f32_16x16x32_bf16 v[116:119], v[152:155], v[192:195], v[116:119]
	v_mfma_f32_16x16x32_bf16 v[108:111], v[160:163], v[192:195], v[108:111]
	v_mfma_f32_16x16x32_bf16 v[100:103], v[152:155], v[200:203], v[100:103]
	v_mfma_f32_16x16x32_bf16 v[92:95], v[160:163], v[200:203], v[92:95]
	v_mfma_f32_16x16x32_bf16 v[84:87], v[152:155], v[208:211], v[84:87]
	v_mfma_f32_16x16x32_bf16 v[76:79], v[160:163], v[208:211], v[76:79]
	v_mfma_f32_16x16x32_bf16 v[124:127], v[156:159], v[188:191], v[124:127]
	v_mfma_f32_16x16x32_bf16 v[120:123], v[164:167], v[188:191], v[120:123]
	v_mfma_f32_16x16x32_bf16 v[116:119], v[156:159], v[196:199], v[116:119]
	v_mfma_f32_16x16x32_bf16 v[108:111], v[164:167], v[196:199], v[108:111]
	v_mfma_f32_16x16x32_bf16 v[100:103], v[156:159], v[204:207], v[100:103]
	v_mfma_f32_16x16x32_bf16 v[92:95], v[164:167], v[204:207], v[92:95]
	v_mfma_f32_16x16x32_bf16 v[84:87], v[156:159], v[212:215], v[84:87]
	v_mfma_f32_16x16x32_bf16 v[76:79], v[164:167], v[212:215], v[76:79]
	v_mfma_f32_16x16x32_bf16 v[112:115], v[168:171], v[184:187], v[112:115]
	v_mfma_f32_16x16x32_bf16 v[104:107], v[176:179], v[184:187], v[104:107]
	v_mfma_f32_16x16x32_bf16 v[96:99], v[168:171], v[192:195], v[96:99]
	v_mfma_f32_16x16x32_bf16 v[88:91], v[176:179], v[192:195], v[88:91]
	v_mfma_f32_16x16x32_bf16 v[80:83], v[168:171], v[200:203], v[80:83]
	v_mfma_f32_16x16x32_bf16 v[72:75], v[176:179], v[200:203], v[72:75]
	v_mfma_f32_16x16x32_bf16 v[68:71], v[168:171], v[208:211], v[68:71]
	v_mfma_f32_16x16x32_bf16 v[64:67], v[176:179], v[208:211], v[64:67]
	v_mfma_f32_16x16x32_bf16 v[112:115], v[172:175], v[188:191], v[112:115]
	v_mfma_f32_16x16x32_bf16 v[104:107], v[180:183], v[188:191], v[104:107]
	v_mfma_f32_16x16x32_bf16 v[96:99], v[172:175], v[196:199], v[96:99]
	v_mfma_f32_16x16x32_bf16 v[88:91], v[180:183], v[196:199], v[88:91]
	v_mfma_f32_16x16x32_bf16 v[80:83], v[172:175], v[204:207], v[80:83]
	v_mfma_f32_16x16x32_bf16 v[72:75], v[180:183], v[204:207], v[72:75]
	v_mfma_f32_16x16x32_bf16 v[68:71], v[172:175], v[212:215], v[68:71]
	v_mfma_f32_16x16x32_bf16 v[64:67], v[180:183], v[212:215], v[64:67]
	s_barrier
	s_add_i32 s37, s37, s55
	v_lshl_add_u64 v[144:145], v[144:145], 0, s[8:9]
	s_mov_b32 m0, s37
	ds_read_b128 v[184:187], v151 offset:49152
	ds_read_b128 v[188:191], v151 offset:50176
	ds_read_b128 v[192:195], v151 offset:51200
	ds_read_b128 v[196:199], v151 offset:52224
	ds_read_b128 v[200:203], v151 offset:53248
	ds_read_b128 v[204:207], v151 offset:54272
	ds_read_b128 v[208:211], v151 offset:55296
	ds_read_b128 v[212:215], v151 offset:56320
	global_load_lds_dwordx4 v[144:145], off
	s_add_i32 m0, s37, 0x2000
	s_add_u32 s38, s50, 0x100080
	v_lshl_add_u64 v[144:145], v[216:217], 0, s[8:9]
	s_addc_u32 s39, s51, 0
	s_add_i32 s37, s40, s55
	global_load_lds_dwordx4 v[144:145], off
	v_lshl_add_u64 v[144:145], s[38:39], 0, v[130:131]
	s_mov_b32 m0, s37
	s_nop 0
	global_load_lds_dwordx4 v[144:145], off
	v_lshl_add_u64 v[144:145], s[38:39], 0, v[134:135]
	s_add_i32 m0, s37, 0x2000
	s_nop 0
	global_load_lds_dwordx4 v[144:145], off
	v_lshl_add_u64 v[144:145], v[218:219], 0, s[8:9]
	s_mov_b32 m0, s60
	s_nop 0
	global_load_lds_dwordx4 v[144:145], off
	v_lshl_add_u64 v[144:145], v[220:221], 0, s[8:9]
	s_mov_b32 m0, s61
	s_nop 0
	global_load_lds_dwordx4 v[144:145], off
	s_waitcnt vmcnt(8)
	s_waitcnt lgkmcnt(0)
	s_barrier
	s_waitcnt lgkmcnt(0)
	v_mfma_f32_16x16x32_bf16 v[60:63], v[152:155], v[184:187], v[60:63]
	v_mfma_f32_16x16x32_bf16 v[56:59], v[160:163], v[184:187], v[56:59]
	v_mfma_f32_16x16x32_bf16 v[52:55], v[152:155], v[192:195], v[52:55]
	v_mfma_f32_16x16x32_bf16 v[44:47], v[160:163], v[192:195], v[44:47]
	v_mfma_f32_16x16x32_bf16 v[36:39], v[152:155], v[200:203], v[36:39]
	v_mfma_f32_16x16x32_bf16 v[28:31], v[160:163], v[200:203], v[28:31]
	v_mfma_f32_16x16x32_bf16 v[20:23], v[152:155], v[208:211], v[20:23]
	v_mfma_f32_16x16x32_bf16 v[12:15], v[160:163], v[208:211], v[12:15]
	v_mfma_f32_16x16x32_bf16 v[60:63], v[156:159], v[188:191], v[60:63]
	v_mfma_f32_16x16x32_bf16 v[56:59], v[164:167], v[188:191], v[56:59]
	v_mfma_f32_16x16x32_bf16 v[52:55], v[156:159], v[196:199], v[52:55]
	v_mfma_f32_16x16x32_bf16 v[44:47], v[164:167], v[196:199], v[44:47]
	v_mfma_f32_16x16x32_bf16 v[36:39], v[156:159], v[204:207], v[36:39]
	v_mfma_f32_16x16x32_bf16 v[28:31], v[164:167], v[204:207], v[28:31]
	v_mfma_f32_16x16x32_bf16 v[20:23], v[156:159], v[212:215], v[20:23]
	v_mfma_f32_16x16x32_bf16 v[12:15], v[164:167], v[212:215], v[12:15]
	v_mfma_f32_16x16x32_bf16 v[48:51], v[168:171], v[184:187], v[48:51]
	v_mfma_f32_16x16x32_bf16 v[40:43], v[176:179], v[184:187], v[40:43]
	v_mfma_f32_16x16x32_bf16 v[32:35], v[168:171], v[192:195], v[32:35]
	v_mfma_f32_16x16x32_bf16 v[24:27], v[176:179], v[192:195], v[24:27]
	v_mfma_f32_16x16x32_bf16 v[16:19], v[168:171], v[200:203], v[16:19]
	v_mfma_f32_16x16x32_bf16 v[8:11], v[176:179], v[200:203], v[8:11]
	v_mfma_f32_16x16x32_bf16 v[4:7], v[168:171], v[208:211], v[4:7]
	v_mfma_f32_16x16x32_bf16 v[0:3], v[176:179], v[208:211], v[0:3]
	v_mfma_f32_16x16x32_bf16 v[48:51], v[172:175], v[188:191], v[48:51]
	v_mfma_f32_16x16x32_bf16 v[40:43], v[180:183], v[188:191], v[40:43]
	v_mfma_f32_16x16x32_bf16 v[32:35], v[172:175], v[196:199], v[32:35]
	v_mfma_f32_16x16x32_bf16 v[24:27], v[180:183], v[196:199], v[24:27]
	v_mfma_f32_16x16x32_bf16 v[16:19], v[172:175], v[204:207], v[16:19]
	v_mfma_f32_16x16x32_bf16 v[8:11], v[180:183], v[204:207], v[8:11]
	v_mfma_f32_16x16x32_bf16 v[4:7], v[172:175], v[212:215], v[4:7]
	v_mfma_f32_16x16x32_bf16 v[0:3], v[180:183], v[212:215], v[0:3]
	s_barrier
	s_add_i32 s36, s36, 2
	s_add_u32 s48, s48, 0x100
	s_addc_u32 s49, s49, 0
	s_add_u32 s34, s34, 0x100
	s_addc_u32 s35, s35, 0
	s_cmp_gt_u32 s36, 61
	s_cbranch_scc0 .LBB0_600
	s_and_b64 vcc, exec, s[10:11]
	s_cbranch_vccz .LBB0_603
	s_barrier

.LBB0_679:
	ds_read_b128 v[144:147], v151
	ds_read_b128 v[154:157], v151 offset:1024
	ds_read_b128 v[158:161], v151 offset:2048
	ds_read_b128 v[162:165], v151 offset:3072
	ds_read_b128 v[166:169], v152
	ds_read_b128 v[170:173], v152 offset:1024
	ds_read_b128 v[174:177], v152 offset:2048
	ds_read_b128 v[178:181], v152 offset:3072
	s_add_u32 s37, s50, 0xfff00080
	s_addc_u32 s38, s51, -1
	s_cmp_eq_u32 s36, 60
	s_cselect_b32 s55, s19, s38
	s_cselect_b32 s54, s66, s37
	s_cselect_b32 s53, s17, s35
	s_cselect_b32 s52, s67, s34
	v_lshl_add_u64 v[214:215], s[50:51], 0, v[136:137]
	s_add_i32 m0, s49, 0xc000
	ds_read_b128 v[182:185], v153
	ds_read_b128 v[186:189], v153 offset:1024
	ds_read_b128 v[190:193], v153 offset:2048
	ds_read_b128 v[194:197], v153 offset:3072
	ds_read_b128 v[198:201], v153 offset:4096
	ds_read_b128 v[202:205], v153 offset:5120
	ds_read_b128 v[206:209], v153 offset:6144
	ds_read_b128 v[210:213], v153 offset:7168
	global_load_lds_dwordx4 v[214:215], off
	v_lshl_add_u64 v[214:215], s[50:51], 0, v[138:139]
	s_add_i32 m0, s49, 0xe000
	s_nop 0
	global_load_lds_dwordx4 v[214:215], off
	s_waitcnt vmcnt(8)
	s_waitcnt lgkmcnt(0)
	s_barrier
	s_waitcnt lgkmcnt(0)
	v_mfma_f32_16x16x32_bf16 v[124:127], v[144:147], v[182:185], v[124:127]
	v_mfma_f32_16x16x32_bf16 v[116:119], v[158:161], v[182:185], v[116:119]
	v_mfma_f32_16x16x32_bf16 v[108:111], v[144:147], v[190:193], v[108:111]
	v_mfma_f32_16x16x32_bf16 v[104:107], v[158:161], v[190:193], v[104:107]
	v_mfma_f32_16x16x32_bf16 v[92:95], v[144:147], v[198:201], v[92:95]
	v_mfma_f32_16x16x32_bf16 v[88:91], v[158:161], v[198:201], v[88:91]
	v_mfma_f32_16x16x32_bf16 v[76:79], v[144:147], v[206:209], v[76:79]
	v_mfma_f32_16x16x32_bf16 v[72:75], v[158:161], v[206:209], v[72:75]
	v_mfma_f32_16x16x32_bf16 v[124:127], v[154:157], v[186:189], v[124:127]
	v_mfma_f32_16x16x32_bf16 v[116:119], v[162:165], v[186:189], v[116:119]
	v_mfma_f32_16x16x32_bf16 v[108:111], v[154:157], v[194:197], v[108:111]
	v_mfma_f32_16x16x32_bf16 v[104:107], v[162:165], v[194:197], v[104:107]
	v_mfma_f32_16x16x32_bf16 v[92:95], v[154:157], v[202:205], v[92:95]
	v_mfma_f32_16x16x32_bf16 v[88:91], v[162:165], v[202:205], v[88:91]
	v_mfma_f32_16x16x32_bf16 v[76:79], v[154:157], v[210:213], v[76:79]
	v_mfma_f32_16x16x32_bf16 v[72:75], v[162:165], v[210:213], v[72:75]
	v_mfma_f32_16x16x32_bf16 v[120:123], v[166:169], v[182:185], v[120:123]
	v_mfma_f32_16x16x32_bf16 v[112:115], v[174:177], v[182:185], v[112:115]
	v_mfma_f32_16x16x32_bf16 v[100:103], v[166:169], v[190:193], v[100:103]
	v_mfma_f32_16x16x32_bf16 v[96:99], v[174:177], v[190:193], v[96:99]
	v_mfma_f32_16x16x32_bf16 v[84:87], v[166:169], v[198:201], v[84:87]
	v_mfma_f32_16x16x32_bf16 v[80:83], v[174:177], v[198:201], v[80:83]
	v_mfma_f32_16x16x32_bf16 v[68:71], v[166:169], v[206:209], v[68:71]
	v_mfma_f32_16x16x32_bf16 v[64:67], v[174:177], v[206:209], v[64:67]
	v_mfma_f32_16x16x32_bf16 v[120:123], v[170:173], v[186:189], v[120:123]
	v_mfma_f32_16x16x32_bf16 v[112:115], v[178:181], v[186:189], v[112:115]
	v_mfma_f32_16x16x32_bf16 v[100:103], v[170:173], v[194:197], v[100:103]
	v_mfma_f32_16x16x32_bf16 v[96:99], v[178:181], v[194:197], v[96:99]
	v_mfma_f32_16x16x32_bf16 v[84:87], v[170:173], v[202:205], v[84:87]
	v_mfma_f32_16x16x32_bf16 v[80:83], v[178:181], v[202:205], v[80:83]
	v_mfma_f32_16x16x32_bf16 v[68:71], v[170:173], v[210:213], v[68:71]
	v_mfma_f32_16x16x32_bf16 v[64:67], v[178:181], v[210:213], v[64:67]
	s_barrier
	s_add_i32 s37, s63, s33
	v_lshl_add_u64 v[214:215], s[52:53], 0, v[130:131]
	s_mov_b32 m0, s37
	ds_read_b128 v[182:185], v153 offset:16384
	ds_read_b128 v[186:189], v153 offset:17408
	ds_read_b128 v[190:193], v153 offset:18432
	ds_read_b128 v[194:197], v153 offset:19456
	ds_read_b128 v[198:201], v153 offset:20480
	ds_read_b128 v[202:205], v153 offset:21504
	ds_read_b128 v[206:209], v153 offset:22528
	ds_read_b128 v[210:213], v153 offset:23552
	global_load_lds_dwordx4 v[214:215], off
	s_add_i32 m0, s37, 0x2000
	s_add_u32 s38, s52, 0x100000
	v_lshl_add_u64 v[216:217], s[52:53], 0, v[134:135]
	s_addc_u32 s39, s53, 0
	s_add_i32 s37, s64, s33
	global_load_lds_dwordx4 v[216:217], off
	v_lshl_add_u64 v[218:219], s[38:39], 0, v[130:131]
	s_mov_b32 m0, s37
	v_lshl_add_u64 v[220:221], s[54:55], 0, v[132:133]
	global_load_lds_dwordx4 v[218:219], off
	v_lshl_add_u64 v[218:219], s[38:39], 0, v[134:135]
	s_add_i32 m0, s37, 0x2000
	s_nop 0
	global_load_lds_dwordx4 v[218:219], off
	v_lshl_add_u64 v[218:219], s[54:55], 0, v[128:129]
	s_mov_b32 m0, s49
	s_nop 0
	global_load_lds_dwordx4 v[218:219], off
	s_mov_b32 m0, s56
	s_nop 0
	global_load_lds_dwordx4 v[220:221], off
	s_waitcnt vmcnt(8)
	s_waitcnt lgkmcnt(0)
	s_barrier
	s_waitcnt lgkmcnt(0)
	v_mfma_f32_16x16x32_bf16 v[60:63], v[144:147], v[182:185], v[60:63]
	v_mfma_f32_16x16x32_bf16 v[56:59], v[158:161], v[182:185], v[56:59]
	v_mfma_f32_16x16x32_bf16 v[44:47], v[144:147], v[190:193], v[44:47]
	v_mfma_f32_16x16x32_bf16 v[40:43], v[158:161], v[190:193], v[40:43]
	v_mfma_f32_16x16x32_bf16 v[28:31], v[144:147], v[198:201], v[28:31]
	v_mfma_f32_16x16x32_bf16 v[24:27], v[158:161], v[198:201], v[24:27]
	v_mfma_f32_16x16x32_bf16 v[12:15], v[144:147], v[206:209], v[12:15]
	v_mfma_f32_16x16x32_bf16 v[8:11], v[158:161], v[206:209], v[8:11]
	v_mfma_f32_16x16x32_bf16 v[60:63], v[154:157], v[186:189], v[60:63]
	v_mfma_f32_16x16x32_bf16 v[56:59], v[162:165], v[186:189], v[56:59]
	v_mfma_f32_16x16x32_bf16 v[44:47], v[154:157], v[194:197], v[44:47]
	v_mfma_f32_16x16x32_bf16 v[40:43], v[162:165], v[194:197], v[40:43]
	v_mfma_f32_16x16x32_bf16 v[28:31], v[154:157], v[202:205], v[28:31]
	v_mfma_f32_16x16x32_bf16 v[24:27], v[162:165], v[202:205], v[24:27]
	v_mfma_f32_16x16x32_bf16 v[12:15], v[154:157], v[210:213], v[12:15]
	v_mfma_f32_16x16x32_bf16 v[8:11], v[162:165], v[210:213], v[8:11]
	v_mfma_f32_16x16x32_bf16 v[52:55], v[166:169], v[182:185], v[52:55]
	v_mfma_f32_16x16x32_bf16 v[48:51], v[174:177], v[182:185], v[48:51]
	v_mfma_f32_16x16x32_bf16 v[36:39], v[166:169], v[190:193], v[36:39]
	v_mfma_f32_16x16x32_bf16 v[32:35], v[174:177], v[190:193], v[32:35]
	v_mfma_f32_16x16x32_bf16 v[20:23], v[166:169], v[198:201], v[20:23]
	v_mfma_f32_16x16x32_bf16 v[16:19], v[174:177], v[198:201], v[16:19]
	v_mfma_f32_16x16x32_bf16 v[4:7], v[166:169], v[206:209], v[4:7]
	v_mfma_f32_16x16x32_bf16 v[0:3], v[174:177], v[206:209], v[0:3]
	v_mfma_f32_16x16x32_bf16 v[52:55], v[170:173], v[186:189], v[52:55]
	v_mfma_f32_16x16x32_bf16 v[48:51], v[178:181], v[186:189], v[48:51]
	v_mfma_f32_16x16x32_bf16 v[36:39], v[170:173], v[194:197], v[36:39]
	v_mfma_f32_16x16x32_bf16 v[32:35], v[178:181], v[194:197], v[32:35]
	v_mfma_f32_16x16x32_bf16 v[20:23], v[170:173], v[202:205], v[20:23]
	v_mfma_f32_16x16x32_bf16 v[16:19], v[178:181], v[202:205], v[16:19]
	v_mfma_f32_16x16x32_bf16 v[4:7], v[170:173], v[210:213], v[4:7]
	v_mfma_f32_16x16x32_bf16 v[0:3], v[178:181], v[210:213], v[0:3]
	s_barrier
	s_add_i32 s37, 0, 0x18000
	s_add_i32 s40, 0, 0x1c000
	v_add_u32_e32 v162, s37, v149
	v_add_u32_e32 v178, s40, v149
	ds_read_b128 v[144:147], v162
	ds_read_b128 v[154:157], v162 offset:1024
	ds_read_b128 v[158:161], v162 offset:2048
	ds_read_b128 v[162:165], v162 offset:3072
	ds_read_b128 v[166:169], v178
	ds_read_b128 v[170:173], v178 offset:1024
	ds_read_b128 v[174:177], v178 offset:2048
	ds_read_b128 v[178:181], v178 offset:3072
	s_add_u32 s38, s54, 0x100000
	s_addc_u32 s39, s55, 0
	s_mov_b32 m0, s57
	v_lshl_add_u64 v[222:223], s[38:39], 0, v[128:129]
	ds_read_b128 v[182:185], v153 offset:32768
	ds_read_b128 v[186:189], v153 offset:33792
	ds_read_b128 v[190:193], v153 offset:34816
	ds_read_b128 v[194:197], v153 offset:35840
	ds_read_b128 v[198:201], v153 offset:36864
	ds_read_b128 v[202:205], v153 offset:37888
	ds_read_b128 v[206:209], v153 offset:38912
	ds_read_b128 v[210:213], v153 offset:39936
	global_load_lds_dwordx4 v[222:223], off
	v_lshl_add_u64 v[222:223], s[38:39], 0, v[132:133]
	s_mov_b32 m0, s58
	s_nop 0
	global_load_lds_dwordx4 v[222:223], off
	s_waitcnt vmcnt(8)
	s_waitcnt lgkmcnt(0)
	s_barrier
	s_waitcnt lgkmcnt(0)
	v_mfma_f32_16x16x32_bf16 v[124:127], v[144:147], v[182:185], v[124:127]
	v_mfma_f32_16x16x32_bf16 v[116:119], v[158:161], v[182:185], v[116:119]
	v_mfma_f32_16x16x32_bf16 v[108:111], v[144:147], v[190:193], v[108:111]
	v_mfma_f32_16x16x32_bf16 v[104:107], v[158:161], v[190:193], v[104:107]
	v_mfma_f32_16x16x32_bf16 v[92:95], v[144:147], v[198:201], v[92:95]
	v_mfma_f32_16x16x32_bf16 v[88:91], v[158:161], v[198:201], v[88:91]
	v_mfma_f32_16x16x32_bf16 v[76:79], v[144:147], v[206:209], v[76:79]
	v_mfma_f32_16x16x32_bf16 v[72:75], v[158:161], v[206:209], v[72:75]
	v_mfma_f32_16x16x32_bf16 v[124:127], v[154:157], v[186:189], v[124:127]
	v_mfma_f32_16x16x32_bf16 v[116:119], v[162:165], v[186:189], v[116:119]
	v_mfma_f32_16x16x32_bf16 v[108:111], v[154:157], v[194:197], v[108:111]
	v_mfma_f32_16x16x32_bf16 v[104:107], v[162:165], v[194:197], v[104:107]
	v_mfma_f32_16x16x32_bf16 v[92:95], v[154:157], v[202:205], v[92:95]
	v_mfma_f32_16x16x32_bf16 v[88:91], v[162:165], v[202:205], v[88:91]
	v_mfma_f32_16x16x32_bf16 v[76:79], v[154:157], v[210:213], v[76:79]
	v_mfma_f32_16x16x32_bf16 v[72:75], v[162:165], v[210:213], v[72:75]
	v_mfma_f32_16x16x32_bf16 v[120:123], v[166:169], v[182:185], v[120:123]
	v_mfma_f32_16x16x32_bf16 v[112:115], v[174:177], v[182:185], v[112:115]
	v_mfma_f32_16x16x32_bf16 v[100:103], v[166:169], v[190:193], v[100:103]
	v_mfma_f32_16x16x32_bf16 v[96:99], v[174:177], v[190:193], v[96:99]
	v_mfma_f32_16x16x32_bf16 v[84:87], v[166:169], v[198:201], v[84:87]
	v_mfma_f32_16x16x32_bf16 v[80:83], v[174:177], v[198:201], v[80:83]
	v_mfma_f32_16x16x32_bf16 v[68:71], v[166:169], v[206:209], v[68:71]
	v_mfma_f32_16x16x32_bf16 v[64:67], v[174:177], v[206:209], v[64:67]
	v_mfma_f32_16x16x32_bf16 v[120:123], v[170:173], v[186:189], v[120:123]
	v_mfma_f32_16x16x32_bf16 v[112:115], v[178:181], v[186:189], v[112:115]
	v_mfma_f32_16x16x32_bf16 v[100:103], v[170:173], v[194:197], v[100:103]
	v_mfma_f32_16x16x32_bf16 v[96:99], v[178:181], v[194:197], v[96:99]
	v_mfma_f32_16x16x32_bf16 v[84:87], v[170:173], v[202:205], v[84:87]
	v_mfma_f32_16x16x32_bf16 v[80:83], v[178:181], v[202:205], v[80:83]
	v_mfma_f32_16x16x32_bf16 v[68:71], v[170:173], v[210:213], v[68:71]
	v_mfma_f32_16x16x32_bf16 v[64:67], v[178:181], v[210:213], v[64:67]
	s_barrier
	s_add_i32 s37, s37, s33
	v_lshl_add_u64 v[214:215], v[214:215], 0, s[10:11]
	s_mov_b32 m0, s37
	ds_read_b128 v[182:185], v153 offset:49152
	ds_read_b128 v[186:189], v153 offset:50176
	ds_read_b128 v[190:193], v153 offset:51200
	ds_read_b128 v[194:197], v153 offset:52224
	ds_read_b128 v[198:201], v153 offset:53248
	ds_read_b128 v[202:205], v153 offset:54272
	ds_read_b128 v[206:209], v153 offset:55296
	ds_read_b128 v[210:213], v153 offset:56320
	global_load_lds_dwordx4 v[214:215], off
	s_add_i32 m0, s37, 0x2000
	s_add_u32 s38, s52, 0x100080
	v_lshl_add_u64 v[214:215], v[216:217], 0, s[10:11]
	s_addc_u32 s39, s53, 0
	s_add_i32 s37, s40, s33
	global_load_lds_dwordx4 v[214:215], off
	v_lshl_add_u64 v[214:215], s[38:39], 0, v[130:131]
	s_mov_b32 m0, s37
	s_nop 0
	global_load_lds_dwordx4 v[214:215], off
	v_lshl_add_u64 v[214:215], s[38:39], 0, v[134:135]
	s_add_i32 m0, s37, 0x2000
	s_nop 0
	global_load_lds_dwordx4 v[214:215], off
	v_lshl_add_u64 v[214:215], v[218:219], 0, s[10:11]
	s_mov_b32 m0, s60
	s_nop 0
	global_load_lds_dwordx4 v[214:215], off
	v_lshl_add_u64 v[214:215], v[220:221], 0, s[10:11]
	s_mov_b32 m0, s61
	s_nop 0
	global_load_lds_dwordx4 v[214:215], off
	s_waitcnt vmcnt(8)
	s_waitcnt lgkmcnt(0)
	s_barrier
	s_waitcnt lgkmcnt(0)
	v_mfma_f32_16x16x32_bf16 v[60:63], v[144:147], v[182:185], v[60:63]
	v_mfma_f32_16x16x32_bf16 v[56:59], v[158:161], v[182:185], v[56:59]
	v_mfma_f32_16x16x32_bf16 v[44:47], v[144:147], v[190:193], v[44:47]
	v_mfma_f32_16x16x32_bf16 v[40:43], v[158:161], v[190:193], v[40:43]
	v_mfma_f32_16x16x32_bf16 v[28:31], v[144:147], v[198:201], v[28:31]
	v_mfma_f32_16x16x32_bf16 v[24:27], v[158:161], v[198:201], v[24:27]
	v_mfma_f32_16x16x32_bf16 v[12:15], v[144:147], v[206:209], v[12:15]
	v_mfma_f32_16x16x32_bf16 v[8:11], v[158:161], v[206:209], v[8:11]
	v_mfma_f32_16x16x32_bf16 v[60:63], v[154:157], v[186:189], v[60:63]
	v_mfma_f32_16x16x32_bf16 v[56:59], v[162:165], v[186:189], v[56:59]
	v_mfma_f32_16x16x32_bf16 v[44:47], v[154:157], v[194:197], v[44:47]
	v_mfma_f32_16x16x32_bf16 v[40:43], v[162:165], v[194:197], v[40:43]
	v_mfma_f32_16x16x32_bf16 v[28:31], v[154:157], v[202:205], v[28:31]
	v_mfma_f32_16x16x32_bf16 v[24:27], v[162:165], v[202:205], v[24:27]
	v_mfma_f32_16x16x32_bf16 v[12:15], v[154:157], v[210:213], v[12:15]
	v_mfma_f32_16x16x32_bf16 v[8:11], v[162:165], v[210:213], v[8:11]
	v_mfma_f32_16x16x32_bf16 v[52:55], v[166:169], v[182:185], v[52:55]
	v_mfma_f32_16x16x32_bf16 v[48:51], v[174:177], v[182:185], v[48:51]
	v_mfma_f32_16x16x32_bf16 v[36:39], v[166:169], v[190:193], v[36:39]
	v_mfma_f32_16x16x32_bf16 v[32:35], v[174:177], v[190:193], v[32:35]
	v_mfma_f32_16x16x32_bf16 v[20:23], v[166:169], v[198:201], v[20:23]
	v_mfma_f32_16x16x32_bf16 v[16:19], v[174:177], v[198:201], v[16:19]
	v_mfma_f32_16x16x32_bf16 v[4:7], v[166:169], v[206:209], v[4:7]
	v_mfma_f32_16x16x32_bf16 v[0:3], v[174:177], v[206:209], v[0:3]
	v_mfma_f32_16x16x32_bf16 v[52:55], v[170:173], v[186:189], v[52:55]
	v_mfma_f32_16x16x32_bf16 v[48:51], v[178:181], v[186:189], v[48:51]
	v_mfma_f32_16x16x32_bf16 v[36:39], v[170:173], v[194:197], v[36:39]
	v_mfma_f32_16x16x32_bf16 v[32:35], v[178:181], v[194:197], v[32:35]
	v_mfma_f32_16x16x32_bf16 v[20:23], v[170:173], v[202:205], v[20:23]
	v_mfma_f32_16x16x32_bf16 v[16:19], v[178:181], v[202:205], v[16:19]
	v_mfma_f32_16x16x32_bf16 v[4:7], v[170:173], v[210:213], v[4:7]
	v_mfma_f32_16x16x32_bf16 v[0:3], v[178:181], v[210:213], v[0:3]
	s_barrier
	s_add_i32 s36, s36, 2
	s_add_u32 s50, s50, 0x100
	s_addc_u32 s51, s51, 0
	s_add_u32 s34, s34, 0x100
	s_addc_u32 s35, s35, 0
	s_cmp_gt_u32 s36, 61
	s_cbranch_scc0 .LBB0_679
	s_and_b64 vcc, exec, s[12:13]
	s_cbranch_vccz .LBB0_682
	s_barrier

.LBB0_758:
	ds_read_b128 v[144:147], v153
	ds_read_b128 v[156:159], v153 offset:1024
	ds_read_b128 v[160:163], v153 offset:2048
	ds_read_b128 v[164:167], v153 offset:3072
	ds_read_b128 v[168:171], v154
	ds_read_b128 v[172:175], v154 offset:1024
	ds_read_b128 v[176:179], v154 offset:2048
	ds_read_b128 v[180:183], v154 offset:3072
	s_add_u32 s37, s38, 0xfff00080
	s_addc_u32 s40, s39, -1
	s_cmp_eq_u32 s36, 60
	s_cselect_b32 s49, s13, s40
	s_cselect_b32 s48, s64, s37
	s_cselect_b32 s47, s11, s35
	s_cselect_b32 s46, s65, s34
	v_lshl_add_u64 v[148:149], s[38:39], 0, v[136:137]
	s_add_i32 m0, s76, 0xc000
	ds_read_b128 v[184:187], v155
	ds_read_b128 v[188:191], v155 offset:1024
	ds_read_b128 v[192:195], v155 offset:2048
	ds_read_b128 v[196:199], v155 offset:3072
	ds_read_b128 v[200:203], v155 offset:4096
	ds_read_b128 v[204:207], v155 offset:5120
	ds_read_b128 v[208:211], v155 offset:6144
	ds_read_b128 v[212:215], v155 offset:7168
	global_load_lds_dwordx4 v[148:149], off
	v_lshl_add_u64 v[148:149], s[38:39], 0, v[138:139]
	s_add_i32 m0, s76, 0xe000
	s_nop 0
	global_load_lds_dwordx4 v[148:149], off
	s_waitcnt vmcnt(8)
	s_waitcnt lgkmcnt(0)
	s_barrier
	s_waitcnt lgkmcnt(0)
	v_mfma_f32_16x16x32_bf16 v[124:127], v[144:147], v[184:187], v[124:127]
	v_mfma_f32_16x16x32_bf16 v[120:123], v[160:163], v[184:187], v[120:123]
	v_mfma_f32_16x16x32_bf16 v[108:111], v[144:147], v[192:195], v[108:111]
	v_mfma_f32_16x16x32_bf16 v[104:107], v[160:163], v[192:195], v[104:107]
	v_mfma_f32_16x16x32_bf16 v[92:95], v[144:147], v[200:203], v[92:95]
	v_mfma_f32_16x16x32_bf16 v[88:91], v[160:163], v[200:203], v[88:91]
	v_mfma_f32_16x16x32_bf16 v[76:79], v[144:147], v[208:211], v[76:79]
	v_mfma_f32_16x16x32_bf16 v[72:75], v[160:163], v[208:211], v[72:75]
	v_mfma_f32_16x16x32_bf16 v[124:127], v[156:159], v[188:191], v[124:127]
	v_mfma_f32_16x16x32_bf16 v[120:123], v[164:167], v[188:191], v[120:123]
	v_mfma_f32_16x16x32_bf16 v[108:111], v[156:159], v[196:199], v[108:111]
	v_mfma_f32_16x16x32_bf16 v[104:107], v[164:167], v[196:199], v[104:107]
	v_mfma_f32_16x16x32_bf16 v[92:95], v[156:159], v[204:207], v[92:95]
	v_mfma_f32_16x16x32_bf16 v[88:91], v[164:167], v[204:207], v[88:91]
	v_mfma_f32_16x16x32_bf16 v[76:79], v[156:159], v[212:215], v[76:79]
	v_mfma_f32_16x16x32_bf16 v[72:75], v[164:167], v[212:215], v[72:75]
	v_mfma_f32_16x16x32_bf16 v[116:119], v[168:171], v[184:187], v[116:119]
	v_mfma_f32_16x16x32_bf16 v[112:115], v[176:179], v[184:187], v[112:115]
	v_mfma_f32_16x16x32_bf16 v[100:103], v[168:171], v[192:195], v[100:103]
	v_mfma_f32_16x16x32_bf16 v[96:99], v[176:179], v[192:195], v[96:99]
	v_mfma_f32_16x16x32_bf16 v[84:87], v[168:171], v[200:203], v[84:87]
	v_mfma_f32_16x16x32_bf16 v[80:83], v[176:179], v[200:203], v[80:83]
	v_mfma_f32_16x16x32_bf16 v[68:71], v[168:171], v[208:211], v[68:71]
	v_mfma_f32_16x16x32_bf16 v[64:67], v[176:179], v[208:211], v[64:67]
	v_mfma_f32_16x16x32_bf16 v[116:119], v[172:175], v[188:191], v[116:119]
	v_mfma_f32_16x16x32_bf16 v[112:115], v[180:183], v[188:191], v[112:115]
	v_mfma_f32_16x16x32_bf16 v[100:103], v[172:175], v[196:199], v[100:103]
	v_mfma_f32_16x16x32_bf16 v[96:99], v[180:183], v[196:199], v[96:99]
	v_mfma_f32_16x16x32_bf16 v[84:87], v[172:175], v[204:207], v[84:87]
	v_mfma_f32_16x16x32_bf16 v[80:83], v[180:183], v[204:207], v[80:83]
	v_mfma_f32_16x16x32_bf16 v[68:71], v[172:175], v[212:215], v[68:71]
	v_mfma_f32_16x16x32_bf16 v[64:67], v[180:183], v[212:215], v[64:67]
	s_barrier
	s_add_i32 s37, s61, s67
	v_lshl_add_u64 v[148:149], s[46:47], 0, v[130:131]
	s_mov_b32 m0, s37
	ds_read_b128 v[184:187], v155 offset:16384
	ds_read_b128 v[188:191], v155 offset:17408
	ds_read_b128 v[192:195], v155 offset:18432
	ds_read_b128 v[196:199], v155 offset:19456
	ds_read_b128 v[200:203], v155 offset:20480
	ds_read_b128 v[204:207], v155 offset:21504
	ds_read_b128 v[208:211], v155 offset:22528
	ds_read_b128 v[212:215], v155 offset:23552
	global_load_lds_dwordx4 v[148:149], off
	s_add_i32 m0, s37, 0x2000
	s_add_u32 s40, s46, 0x100000
	v_lshl_add_u64 v[216:217], s[46:47], 0, v[134:135]
	s_addc_u32 s41, s47, 0
	s_add_i32 s37, s62, s67
	global_load_lds_dwordx4 v[216:217], off
	v_lshl_add_u64 v[218:219], s[40:41], 0, v[130:131]
	s_mov_b32 m0, s37
	v_lshl_add_u64 v[220:221], s[48:49], 0, v[132:133]
	global_load_lds_dwordx4 v[218:219], off
	v_lshl_add_u64 v[218:219], s[40:41], 0, v[134:135]
	s_add_i32 m0, s37, 0x2000
	s_nop 0
	global_load_lds_dwordx4 v[218:219], off
	v_lshl_add_u64 v[218:219], s[48:49], 0, v[128:129]
	s_mov_b32 m0, s76
	s_nop 0
	global_load_lds_dwordx4 v[218:219], off
	s_mov_b32 m0, s52
	s_nop 0
	global_load_lds_dwordx4 v[220:221], off
	s_waitcnt vmcnt(8)
	s_waitcnt lgkmcnt(0)
	s_barrier
	s_waitcnt lgkmcnt(0)
	v_mfma_f32_16x16x32_bf16 v[60:63], v[144:147], v[184:187], v[60:63]
	v_mfma_f32_16x16x32_bf16 v[56:59], v[160:163], v[184:187], v[56:59]
	v_mfma_f32_16x16x32_bf16 v[44:47], v[144:147], v[192:195], v[44:47]
	v_mfma_f32_16x16x32_bf16 v[40:43], v[160:163], v[192:195], v[40:43]
	v_mfma_f32_16x16x32_bf16 v[28:31], v[144:147], v[200:203], v[28:31]
	v_mfma_f32_16x16x32_bf16 v[24:27], v[160:163], v[200:203], v[24:27]
	v_mfma_f32_16x16x32_bf16 v[12:15], v[144:147], v[208:211], v[12:15]
	v_mfma_f32_16x16x32_bf16 v[8:11], v[160:163], v[208:211], v[8:11]
	v_mfma_f32_16x16x32_bf16 v[60:63], v[156:159], v[188:191], v[60:63]
	v_mfma_f32_16x16x32_bf16 v[56:59], v[164:167], v[188:191], v[56:59]
	v_mfma_f32_16x16x32_bf16 v[44:47], v[156:159], v[196:199], v[44:47]
	v_mfma_f32_16x16x32_bf16 v[40:43], v[164:167], v[196:199], v[40:43]
	v_mfma_f32_16x16x32_bf16 v[28:31], v[156:159], v[204:207], v[28:31]
	v_mfma_f32_16x16x32_bf16 v[24:27], v[164:167], v[204:207], v[24:27]
	v_mfma_f32_16x16x32_bf16 v[12:15], v[156:159], v[212:215], v[12:15]
	v_mfma_f32_16x16x32_bf16 v[8:11], v[164:167], v[212:215], v[8:11]
	v_mfma_f32_16x16x32_bf16 v[52:55], v[168:171], v[184:187], v[52:55]
	v_mfma_f32_16x16x32_bf16 v[48:51], v[176:179], v[184:187], v[48:51]
	v_mfma_f32_16x16x32_bf16 v[36:39], v[168:171], v[192:195], v[36:39]
	v_mfma_f32_16x16x32_bf16 v[32:35], v[176:179], v[192:195], v[32:35]
	v_mfma_f32_16x16x32_bf16 v[20:23], v[168:171], v[200:203], v[20:23]
	v_mfma_f32_16x16x32_bf16 v[16:19], v[176:179], v[200:203], v[16:19]
	v_mfma_f32_16x16x32_bf16 v[4:7], v[168:171], v[208:211], v[4:7]
	v_mfma_f32_16x16x32_bf16 v[0:3], v[176:179], v[208:211], v[0:3]
	v_mfma_f32_16x16x32_bf16 v[52:55], v[172:175], v[188:191], v[52:55]
	v_mfma_f32_16x16x32_bf16 v[48:51], v[180:183], v[188:191], v[48:51]
	v_mfma_f32_16x16x32_bf16 v[36:39], v[172:175], v[196:199], v[36:39]
	v_mfma_f32_16x16x32_bf16 v[32:35], v[180:183], v[196:199], v[32:35]
	v_mfma_f32_16x16x32_bf16 v[20:23], v[172:175], v[204:207], v[20:23]
	v_mfma_f32_16x16x32_bf16 v[16:19], v[180:183], v[204:207], v[16:19]
	v_mfma_f32_16x16x32_bf16 v[4:7], v[172:175], v[212:215], v[4:7]
	v_mfma_f32_16x16x32_bf16 v[0:3], v[180:183], v[212:215], v[0:3]
	s_barrier
	s_add_i32 s37, 0, 0x18000
	s_add_i32 s42, 0, 0x1c000
	v_add_u32_e32 v164, s37, v151
	v_add_u32_e32 v180, s42, v151
	ds_read_b128 v[144:147], v164
	ds_read_b128 v[156:159], v164 offset:1024
	ds_read_b128 v[160:163], v164 offset:2048
	ds_read_b128 v[164:167], v164 offset:3072
	ds_read_b128 v[168:171], v180
	ds_read_b128 v[172:175], v180 offset:1024
	ds_read_b128 v[176:179], v180 offset:2048
	ds_read_b128 v[180:183], v180 offset:3072
	s_add_u32 s40, s48, 0x100000
	s_addc_u32 s41, s49, 0
	s_mov_b32 m0, s53
	v_lshl_add_u64 v[222:223], s[40:41], 0, v[128:129]
	ds_read_b128 v[184:187], v155 offset:32768
	ds_read_b128 v[188:191], v155 offset:33792
	ds_read_b128 v[192:195], v155 offset:34816
	ds_read_b128 v[196:199], v155 offset:35840
	ds_read_b128 v[200:203], v155 offset:36864
	ds_read_b128 v[204:207], v155 offset:37888
	ds_read_b128 v[208:211], v155 offset:38912
	ds_read_b128 v[212:215], v155 offset:39936
	global_load_lds_dwordx4 v[222:223], off
	v_lshl_add_u64 v[222:223], s[40:41], 0, v[132:133]
	s_mov_b32 m0, s54
	s_nop 0
	global_load_lds_dwordx4 v[222:223], off
	s_waitcnt vmcnt(8)
	s_waitcnt lgkmcnt(0)
	s_barrier
	s_waitcnt lgkmcnt(0)
	v_mfma_f32_16x16x32_bf16 v[124:127], v[144:147], v[184:187], v[124:127]
	v_mfma_f32_16x16x32_bf16 v[120:123], v[160:163], v[184:187], v[120:123]
	v_mfma_f32_16x16x32_bf16 v[108:111], v[144:147], v[192:195], v[108:111]
	v_mfma_f32_16x16x32_bf16 v[104:107], v[160:163], v[192:195], v[104:107]
	v_mfma_f32_16x16x32_bf16 v[92:95], v[144:147], v[200:203], v[92:95]
	v_mfma_f32_16x16x32_bf16 v[88:91], v[160:163], v[200:203], v[88:91]
	v_mfma_f32_16x16x32_bf16 v[76:79], v[144:147], v[208:211], v[76:79]
	v_mfma_f32_16x16x32_bf16 v[72:75], v[160:163], v[208:211], v[72:75]
	v_mfma_f32_16x16x32_bf16 v[124:127], v[156:159], v[188:191], v[124:127]
	v_mfma_f32_16x16x32_bf16 v[120:123], v[164:167], v[188:191], v[120:123]
	v_mfma_f32_16x16x32_bf16 v[108:111], v[156:159], v[196:199], v[108:111]
	v_mfma_f32_16x16x32_bf16 v[104:107], v[164:167], v[196:199], v[104:107]
	v_mfma_f32_16x16x32_bf16 v[92:95], v[156:159], v[204:207], v[92:95]
	v_mfma_f32_16x16x32_bf16 v[88:91], v[164:167], v[204:207], v[88:91]
	v_mfma_f32_16x16x32_bf16 v[76:79], v[156:159], v[212:215], v[76:79]
	v_mfma_f32_16x16x32_bf16 v[72:75], v[164:167], v[212:215], v[72:75]
	v_mfma_f32_16x16x32_bf16 v[116:119], v[168:171], v[184:187], v[116:119]
	v_mfma_f32_16x16x32_bf16 v[112:115], v[176:179], v[184:187], v[112:115]
	v_mfma_f32_16x16x32_bf16 v[100:103], v[168:171], v[192:195], v[100:103]
	v_mfma_f32_16x16x32_bf16 v[96:99], v[176:179], v[192:195], v[96:99]
	v_mfma_f32_16x16x32_bf16 v[84:87], v[168:171], v[200:203], v[84:87]
	v_mfma_f32_16x16x32_bf16 v[80:83], v[176:179], v[200:203], v[80:83]
	v_mfma_f32_16x16x32_bf16 v[68:71], v[168:171], v[208:211], v[68:71]
	v_mfma_f32_16x16x32_bf16 v[64:67], v[176:179], v[208:211], v[64:67]
	v_mfma_f32_16x16x32_bf16 v[116:119], v[172:175], v[188:191], v[116:119]
	v_mfma_f32_16x16x32_bf16 v[112:115], v[180:183], v[188:191], v[112:115]
	v_mfma_f32_16x16x32_bf16 v[100:103], v[172:175], v[196:199], v[100:103]
	v_mfma_f32_16x16x32_bf16 v[96:99], v[180:183], v[196:199], v[96:99]
	v_mfma_f32_16x16x32_bf16 v[84:87], v[172:175], v[204:207], v[84:87]
	v_mfma_f32_16x16x32_bf16 v[80:83], v[180:183], v[204:207], v[80:83]
	v_mfma_f32_16x16x32_bf16 v[68:71], v[172:175], v[212:215], v[68:71]
	v_mfma_f32_16x16x32_bf16 v[64:67], v[180:183], v[212:215], v[64:67]
	s_barrier
	s_add_i32 s37, s37, s67
	v_lshl_add_u64 v[148:149], v[148:149], 0, s[6:7]
	s_mov_b32 m0, s37
	ds_read_b128 v[184:187], v155 offset:49152
	ds_read_b128 v[188:191], v155 offset:50176
	ds_read_b128 v[192:195], v155 offset:51200
	ds_read_b128 v[196:199], v155 offset:52224
	ds_read_b128 v[200:203], v155 offset:53248
	ds_read_b128 v[204:207], v155 offset:54272
	ds_read_b128 v[208:211], v155 offset:55296
	ds_read_b128 v[212:215], v155 offset:56320
	global_load_lds_dwordx4 v[148:149], off
	s_add_i32 m0, s37, 0x2000
	s_add_u32 s40, s46, 0x100080
	v_lshl_add_u64 v[148:149], v[216:217], 0, s[6:7]
	s_addc_u32 s41, s47, 0
	s_add_i32 s37, s42, s67
	global_load_lds_dwordx4 v[148:149], off
	v_lshl_add_u64 v[148:149], s[40:41], 0, v[130:131]
	s_mov_b32 m0, s37
	s_nop 0
	global_load_lds_dwordx4 v[148:149], off
	v_lshl_add_u64 v[148:149], s[40:41], 0, v[134:135]
	s_add_i32 m0, s37, 0x2000
	s_nop 0
	global_load_lds_dwordx4 v[148:149], off
	v_lshl_add_u64 v[148:149], v[218:219], 0, s[6:7]
	s_mov_b32 m0, s56
	s_nop 0
	global_load_lds_dwordx4 v[148:149], off
	v_lshl_add_u64 v[148:149], v[220:221], 0, s[6:7]
	s_mov_b32 m0, s57
	s_nop 0
	global_load_lds_dwordx4 v[148:149], off
	s_waitcnt vmcnt(8)
	s_waitcnt lgkmcnt(0)
	s_barrier
	s_waitcnt lgkmcnt(0)
	v_mfma_f32_16x16x32_bf16 v[60:63], v[144:147], v[184:187], v[60:63]
	v_mfma_f32_16x16x32_bf16 v[56:59], v[160:163], v[184:187], v[56:59]
	v_mfma_f32_16x16x32_bf16 v[44:47], v[144:147], v[192:195], v[44:47]
	v_mfma_f32_16x16x32_bf16 v[40:43], v[160:163], v[192:195], v[40:43]
	v_mfma_f32_16x16x32_bf16 v[28:31], v[144:147], v[200:203], v[28:31]
	v_mfma_f32_16x16x32_bf16 v[24:27], v[160:163], v[200:203], v[24:27]
	v_mfma_f32_16x16x32_bf16 v[12:15], v[144:147], v[208:211], v[12:15]
	v_mfma_f32_16x16x32_bf16 v[8:11], v[160:163], v[208:211], v[8:11]
	v_mfma_f32_16x16x32_bf16 v[60:63], v[156:159], v[188:191], v[60:63]
	v_mfma_f32_16x16x32_bf16 v[56:59], v[164:167], v[188:191], v[56:59]
	v_mfma_f32_16x16x32_bf16 v[44:47], v[156:159], v[196:199], v[44:47]
	v_mfma_f32_16x16x32_bf16 v[40:43], v[164:167], v[196:199], v[40:43]
	v_mfma_f32_16x16x32_bf16 v[28:31], v[156:159], v[204:207], v[28:31]
	v_mfma_f32_16x16x32_bf16 v[24:27], v[164:167], v[204:207], v[24:27]
	v_mfma_f32_16x16x32_bf16 v[12:15], v[156:159], v[212:215], v[12:15]
	v_mfma_f32_16x16x32_bf16 v[8:11], v[164:167], v[212:215], v[8:11]
	v_mfma_f32_16x16x32_bf16 v[52:55], v[168:171], v[184:187], v[52:55]
	v_mfma_f32_16x16x32_bf16 v[48:51], v[176:179], v[184:187], v[48:51]
	v_mfma_f32_16x16x32_bf16 v[36:39], v[168:171], v[192:195], v[36:39]
	v_mfma_f32_16x16x32_bf16 v[32:35], v[176:179], v[192:195], v[32:35]
	v_mfma_f32_16x16x32_bf16 v[20:23], v[168:171], v[200:203], v[20:23]
	v_mfma_f32_16x16x32_bf16 v[16:19], v[176:179], v[200:203], v[16:19]
	v_mfma_f32_16x16x32_bf16 v[4:7], v[168:171], v[208:211], v[4:7]
	v_mfma_f32_16x16x32_bf16 v[0:3], v[176:179], v[208:211], v[0:3]
	v_mfma_f32_16x16x32_bf16 v[52:55], v[172:175], v[188:191], v[52:55]
	v_mfma_f32_16x16x32_bf16 v[48:51], v[180:183], v[188:191], v[48:51]
	v_mfma_f32_16x16x32_bf16 v[36:39], v[172:175], v[196:199], v[36:39]
	v_mfma_f32_16x16x32_bf16 v[32:35], v[180:183], v[196:199], v[32:35]
	v_mfma_f32_16x16x32_bf16 v[20:23], v[172:175], v[204:207], v[20:23]
	v_mfma_f32_16x16x32_bf16 v[16:19], v[180:183], v[204:207], v[16:19]
	v_mfma_f32_16x16x32_bf16 v[4:7], v[172:175], v[212:215], v[4:7]
	v_mfma_f32_16x16x32_bf16 v[0:3], v[180:183], v[212:215], v[0:3]
	s_barrier
	s_add_i32 s36, s36, 2
	s_add_u32 s38, s38, 0x100
	s_addc_u32 s39, s39, 0
	s_add_u32 s34, s34, 0x100
	s_addc_u32 s35, s35, 0
	s_cmp_gt_u32 s36, 61
	s_cbranch_scc0 .LBB0_758
	s_and_b64 vcc, exec, s[8:9]
	s_cbranch_vccz .LBB0_761
	s_barrier

.LBB0_914:
	ds_read_b128 v[128:131], v187
	ds_read_b128 v[132:135], v187 offset:1024
	ds_read_b128 v[136:139], v187 offset:2048
	ds_read_b128 v[140:143], v187 offset:3072
	ds_read_b128 v[144:147], v188
	ds_read_b128 v[148:151], v188 offset:1024
	ds_read_b128 v[152:155], v188 offset:2048
	ds_read_b128 v[156:159], v188 offset:3072
	s_add_u32 s52, s50, 0x100
	s_addc_u32 s53, s51, 0
	s_cmp_eq_u32 s96, 60
	s_cselect_b32 s57, s41, s53
	s_cselect_b32 s56, s47, s52
	s_cselect_b32 s55, s39, s49
	s_cselect_b32 s54, s34, s35
	v_lshl_add_u64 v[160:161], s[50:51], 0, v[170:171]
	s_add_i32 m0, s67, 0xc000
	ds_read_b128 v[178:181], v189
	ds_read_b128 v[192:195], v189 offset:1024
	ds_read_b128 v[196:199], v189 offset:2048
	ds_read_b128 v[200:203], v189 offset:3072
	ds_read_b128 v[204:207], v189 offset:4096
	ds_read_b128 v[208:211], v189 offset:5120
	ds_read_b128 v[212:215], v189 offset:6144
	ds_read_b128 v[216:219], v189 offset:7168
	global_load_lds_dwordx4 v[160:161], off
	v_lshl_add_u64 v[160:161], s[50:51], 0, v[172:173]
	s_add_i32 m0, s67, 0xe000
	s_nop 0
	global_load_lds_dwordx4 v[160:161], off
	s_waitcnt vmcnt(8)
	s_waitcnt lgkmcnt(0)
	s_barrier
	s_waitcnt lgkmcnt(0)
	v_mfma_f32_16x16x32_bf16 v[124:127], v[128:131], v[178:181], v[124:127]
	v_mfma_f32_16x16x32_bf16 v[60:63], v[136:139], v[178:181], v[60:63]
	v_mfma_f32_16x16x32_bf16 v[116:119], v[128:131], v[196:199], v[116:119]
	v_mfma_f32_16x16x32_bf16 v[56:59], v[136:139], v[196:199], v[56:59]
	v_mfma_f32_16x16x32_bf16 v[108:111], v[128:131], v[204:207], v[108:111]
	v_mfma_f32_16x16x32_bf16 v[44:47], v[136:139], v[204:207], v[44:47]
	v_mfma_f32_16x16x32_bf16 v[104:107], v[128:131], v[212:215], v[104:107]
	v_mfma_f32_16x16x32_bf16 v[40:43], v[136:139], v[212:215], v[40:43]
	v_mfma_f32_16x16x32_bf16 v[124:127], v[132:135], v[192:195], v[124:127]
	v_mfma_f32_16x16x32_bf16 v[60:63], v[140:143], v[192:195], v[60:63]
	v_mfma_f32_16x16x32_bf16 v[116:119], v[132:135], v[200:203], v[116:119]
	v_mfma_f32_16x16x32_bf16 v[56:59], v[140:143], v[200:203], v[56:59]
	v_mfma_f32_16x16x32_bf16 v[108:111], v[132:135], v[208:211], v[108:111]
	v_mfma_f32_16x16x32_bf16 v[44:47], v[140:143], v[208:211], v[44:47]
	v_mfma_f32_16x16x32_bf16 v[104:107], v[132:135], v[216:219], v[104:107]
	v_mfma_f32_16x16x32_bf16 v[40:43], v[140:143], v[216:219], v[40:43]
	v_mfma_f32_16x16x32_bf16 v[120:123], v[144:147], v[178:181], v[120:123]
	v_mfma_f32_16x16x32_bf16 v[52:55], v[152:155], v[178:181], v[52:55]
	v_mfma_f32_16x16x32_bf16 v[112:115], v[144:147], v[196:199], v[112:115]
	v_mfma_f32_16x16x32_bf16 v[48:51], v[152:155], v[196:199], v[48:51]
	v_mfma_f32_16x16x32_bf16 v[100:103], v[144:147], v[204:207], v[100:103]
	v_mfma_f32_16x16x32_bf16 v[36:39], v[152:155], v[204:207], v[36:39]
	v_mfma_f32_16x16x32_bf16 v[96:99], v[144:147], v[212:215], v[96:99]
	v_mfma_f32_16x16x32_bf16 v[32:35], v[152:155], v[212:215], v[32:35]
	v_mfma_f32_16x16x32_bf16 v[120:123], v[148:151], v[192:195], v[120:123]
	v_mfma_f32_16x16x32_bf16 v[52:55], v[156:159], v[192:195], v[52:55]
	v_mfma_f32_16x16x32_bf16 v[112:115], v[148:151], v[200:203], v[112:115]
	v_mfma_f32_16x16x32_bf16 v[48:51], v[156:159], v[200:203], v[48:51]
	v_mfma_f32_16x16x32_bf16 v[100:103], v[148:151], v[208:211], v[100:103]
	v_mfma_f32_16x16x32_bf16 v[36:39], v[156:159], v[208:211], v[36:39]
	v_mfma_f32_16x16x32_bf16 v[96:99], v[148:151], v[216:219], v[96:99]
	v_mfma_f32_16x16x32_bf16 v[32:35], v[156:159], v[216:219], v[32:35]
	s_barrier
	s_add_i32 s50, s92, s66
	v_lshl_add_u64 v[160:161], s[54:55], 0, v[164:165]
	s_mov_b32 m0, s50
	ds_read_b128 v[178:181], v189 offset:16384
	ds_read_b128 v[192:195], v189 offset:17408
	ds_read_b128 v[196:199], v189 offset:18432
	ds_read_b128 v[200:203], v189 offset:19456
	ds_read_b128 v[204:207], v189 offset:20480
	ds_read_b128 v[208:211], v189 offset:21504
	ds_read_b128 v[212:215], v189 offset:22528
	ds_read_b128 v[216:219], v189 offset:23552
	global_load_lds_dwordx4 v[160:161], off
	s_add_i32 m0, s50, 0x2000
	s_add_u32 s50, s54, 0x100000
	v_lshl_add_u64 v[182:183], s[54:55], 0, v[168:169]
	s_addc_u32 s51, s55, 0
	s_add_i32 s97, s93, s66
	global_load_lds_dwordx4 v[182:183], off
	v_lshl_add_u64 v[220:221], s[50:51], 0, v[164:165]
	s_mov_b32 m0, s97
	v_lshl_add_u64 v[222:223], s[56:57], 0, v[166:167]
	global_load_lds_dwordx4 v[220:221], off
	v_lshl_add_u64 v[220:221], s[50:51], 0, v[168:169]
	s_add_i32 m0, s97, 0x2000
	s_nop 0
	global_load_lds_dwordx4 v[220:221], off
	v_lshl_add_u64 v[220:221], s[56:57], 0, v[162:163]
	s_mov_b32 m0, s67
	s_nop 0
	global_load_lds_dwordx4 v[220:221], off
	s_mov_b32 m0, s68
	s_nop 0
	global_load_lds_dwordx4 v[222:223], off
	s_waitcnt vmcnt(8)
	s_waitcnt lgkmcnt(0)
	s_barrier
	s_waitcnt lgkmcnt(0)
	v_mfma_f32_16x16x32_bf16 v[92:95], v[128:131], v[178:181], v[92:95]
	v_mfma_f32_16x16x32_bf16 v[28:31], v[136:139], v[178:181], v[28:31]
	v_mfma_f32_16x16x32_bf16 v[84:87], v[128:131], v[196:199], v[84:87]
	v_mfma_f32_16x16x32_bf16 v[24:27], v[136:139], v[196:199], v[24:27]
	v_mfma_f32_16x16x32_bf16 v[76:79], v[128:131], v[204:207], v[76:79]
	v_mfma_f32_16x16x32_bf16 v[12:15], v[136:139], v[204:207], v[12:15]
	v_mfma_f32_16x16x32_bf16 v[72:75], v[128:131], v[212:215], v[72:75]
	v_mfma_f32_16x16x32_bf16 v[8:11], v[136:139], v[212:215], v[8:11]
	v_mfma_f32_16x16x32_bf16 v[92:95], v[132:135], v[192:195], v[92:95]
	v_mfma_f32_16x16x32_bf16 v[28:31], v[140:143], v[192:195], v[28:31]
	v_mfma_f32_16x16x32_bf16 v[84:87], v[132:135], v[200:203], v[84:87]
	v_mfma_f32_16x16x32_bf16 v[24:27], v[140:143], v[200:203], v[24:27]
	v_mfma_f32_16x16x32_bf16 v[76:79], v[132:135], v[208:211], v[76:79]
	v_mfma_f32_16x16x32_bf16 v[12:15], v[140:143], v[208:211], v[12:15]
	v_mfma_f32_16x16x32_bf16 v[72:75], v[132:135], v[216:219], v[72:75]
	v_mfma_f32_16x16x32_bf16 v[8:11], v[140:143], v[216:219], v[8:11]
	v_mfma_f32_16x16x32_bf16 v[88:91], v[144:147], v[178:181], v[88:91]
	v_mfma_f32_16x16x32_bf16 v[20:23], v[152:155], v[178:181], v[20:23]
	v_mfma_f32_16x16x32_bf16 v[80:83], v[144:147], v[196:199], v[80:83]
	v_mfma_f32_16x16x32_bf16 v[16:19], v[152:155], v[196:199], v[16:19]
	v_mfma_f32_16x16x32_bf16 v[68:71], v[144:147], v[204:207], v[68:71]
	v_mfma_f32_16x16x32_bf16 v[4:7], v[152:155], v[204:207], v[4:7]
	v_mfma_f32_16x16x32_bf16 v[64:67], v[144:147], v[212:215], v[64:67]
	v_mfma_f32_16x16x32_bf16 v[0:3], v[152:155], v[212:215], v[0:3]
	v_mfma_f32_16x16x32_bf16 v[88:91], v[148:151], v[192:195], v[88:91]
	v_mfma_f32_16x16x32_bf16 v[20:23], v[156:159], v[192:195], v[20:23]
	v_mfma_f32_16x16x32_bf16 v[80:83], v[148:151], v[200:203], v[80:83]
	v_mfma_f32_16x16x32_bf16 v[16:19], v[156:159], v[200:203], v[16:19]
	v_mfma_f32_16x16x32_bf16 v[68:71], v[148:151], v[208:211], v[68:71]
	v_mfma_f32_16x16x32_bf16 v[4:7], v[156:159], v[208:211], v[4:7]
	v_mfma_f32_16x16x32_bf16 v[64:67], v[148:151], v[216:219], v[64:67]
	v_mfma_f32_16x16x32_bf16 v[0:3], v[156:159], v[216:219], v[0:3]
	s_barrier
	s_add_i32 s97, 0, 0x18000
	s_add_i32 vcc_lo, 0, 0x1c000
	v_add_u32_e32 v140, s97, v184
	v_add_u32_e32 v156, vcc_lo, v184
	ds_read_b128 v[128:131], v140
	ds_read_b128 v[132:135], v140 offset:1024
	ds_read_b128 v[136:139], v140 offset:2048
	ds_read_b128 v[140:143], v140 offset:3072
	ds_read_b128 v[144:147], v156
	ds_read_b128 v[148:151], v156 offset:1024
	ds_read_b128 v[152:155], v156 offset:2048
	ds_read_b128 v[156:159], v156 offset:3072
	s_add_u32 s50, s56, 0x100000
	s_addc_u32 s51, s57, 0
	s_mov_b32 m0, s69
	v_lshl_add_u64 v[226:227], s[50:51], 0, v[162:163]
	ds_read_b128 v[178:181], v189 offset:32768
	ds_read_b128 v[192:195], v189 offset:33792
	ds_read_b128 v[196:199], v189 offset:34816
	ds_read_b128 v[200:203], v189 offset:35840
	ds_read_b128 v[204:207], v189 offset:36864
	ds_read_b128 v[208:211], v189 offset:37888
	ds_read_b128 v[212:215], v189 offset:38912
	ds_read_b128 v[216:219], v189 offset:39936
	global_load_lds_dwordx4 v[226:227], off
	v_lshl_add_u64 v[226:227], s[50:51], 0, v[166:167]
	s_mov_b32 m0, s76
	s_nop 0
	global_load_lds_dwordx4 v[226:227], off
	s_waitcnt vmcnt(8)
	s_waitcnt lgkmcnt(0)
	s_barrier
	s_waitcnt lgkmcnt(0)
	v_mfma_f32_16x16x32_bf16 v[124:127], v[128:131], v[178:181], v[124:127]
	v_mfma_f32_16x16x32_bf16 v[60:63], v[136:139], v[178:181], v[60:63]
	v_mfma_f32_16x16x32_bf16 v[116:119], v[128:131], v[196:199], v[116:119]
	v_mfma_f32_16x16x32_bf16 v[56:59], v[136:139], v[196:199], v[56:59]
	v_mfma_f32_16x16x32_bf16 v[108:111], v[128:131], v[204:207], v[108:111]
	v_mfma_f32_16x16x32_bf16 v[44:47], v[136:139], v[204:207], v[44:47]
	v_mfma_f32_16x16x32_bf16 v[104:107], v[128:131], v[212:215], v[104:107]
	v_mfma_f32_16x16x32_bf16 v[40:43], v[136:139], v[212:215], v[40:43]
	v_mfma_f32_16x16x32_bf16 v[124:127], v[132:135], v[192:195], v[124:127]
	v_mfma_f32_16x16x32_bf16 v[60:63], v[140:143], v[192:195], v[60:63]
	v_mfma_f32_16x16x32_bf16 v[116:119], v[132:135], v[200:203], v[116:119]
	v_mfma_f32_16x16x32_bf16 v[56:59], v[140:143], v[200:203], v[56:59]
	v_mfma_f32_16x16x32_bf16 v[108:111], v[132:135], v[208:211], v[108:111]
	v_mfma_f32_16x16x32_bf16 v[44:47], v[140:143], v[208:211], v[44:47]
	v_mfma_f32_16x16x32_bf16 v[104:107], v[132:135], v[216:219], v[104:107]
	v_mfma_f32_16x16x32_bf16 v[40:43], v[140:143], v[216:219], v[40:43]
	v_mfma_f32_16x16x32_bf16 v[120:123], v[144:147], v[178:181], v[120:123]
	v_mfma_f32_16x16x32_bf16 v[52:55], v[152:155], v[178:181], v[52:55]
	v_mfma_f32_16x16x32_bf16 v[112:115], v[144:147], v[196:199], v[112:115]
	v_mfma_f32_16x16x32_bf16 v[48:51], v[152:155], v[196:199], v[48:51]
	v_mfma_f32_16x16x32_bf16 v[100:103], v[144:147], v[204:207], v[100:103]
	v_mfma_f32_16x16x32_bf16 v[36:39], v[152:155], v[204:207], v[36:39]
	v_mfma_f32_16x16x32_bf16 v[96:99], v[144:147], v[212:215], v[96:99]
	v_mfma_f32_16x16x32_bf16 v[32:35], v[152:155], v[212:215], v[32:35]
	v_mfma_f32_16x16x32_bf16 v[120:123], v[148:151], v[192:195], v[120:123]
	v_mfma_f32_16x16x32_bf16 v[52:55], v[156:159], v[192:195], v[52:55]
	v_mfma_f32_16x16x32_bf16 v[112:115], v[148:151], v[200:203], v[112:115]
	v_mfma_f32_16x16x32_bf16 v[48:51], v[156:159], v[200:203], v[48:51]
	v_mfma_f32_16x16x32_bf16 v[100:103], v[148:151], v[208:211], v[100:103]
	v_mfma_f32_16x16x32_bf16 v[36:39], v[156:159], v[208:211], v[36:39]
	v_mfma_f32_16x16x32_bf16 v[96:99], v[148:151], v[216:219], v[96:99]
	v_mfma_f32_16x16x32_bf16 v[32:35], v[156:159], v[216:219], v[32:35]
	s_barrier
	s_add_i32 s50, s97, s66
	v_lshl_add_u64 v[160:161], v[160:161], 0, s[10:11]
	s_mov_b32 m0, s50
	ds_read_b128 v[178:181], v189 offset:49152
	ds_read_b128 v[192:195], v189 offset:50176
	ds_read_b128 v[196:199], v189 offset:51200
	ds_read_b128 v[200:203], v189 offset:52224
	ds_read_b128 v[204:207], v189 offset:53248
	ds_read_b128 v[208:211], v189 offset:54272
	ds_read_b128 v[212:215], v189 offset:55296
	ds_read_b128 v[216:219], v189 offset:56320
	global_load_lds_dwordx4 v[160:161], off
	s_add_i32 m0, s50, 0x2000
	s_add_u32 s50, s54, 0x100080
	v_lshl_add_u64 v[160:161], v[182:183], 0, s[10:11]
	s_addc_u32 s51, s55, 0
	s_add_i32 s54, vcc_lo, s66
	global_load_lds_dwordx4 v[160:161], off
	v_lshl_add_u64 v[160:161], s[50:51], 0, v[164:165]
	s_mov_b32 m0, s54
	s_nop 0
	global_load_lds_dwordx4 v[160:161], off
	v_lshl_add_u64 v[160:161], s[50:51], 0, v[168:169]
	s_add_i32 m0, s54, 0x2000
	s_nop 0
	global_load_lds_dwordx4 v[160:161], off
	v_lshl_add_u64 v[160:161], v[220:221], 0, s[10:11]
	s_mov_b32 m0, s84
	s_nop 0
	global_load_lds_dwordx4 v[160:161], off
	v_lshl_add_u64 v[160:161], v[222:223], 0, s[10:11]
	s_mov_b32 m0, s85
	s_nop 0
	global_load_lds_dwordx4 v[160:161], off
	s_waitcnt vmcnt(8)
	s_waitcnt lgkmcnt(0)
	s_barrier
	s_waitcnt lgkmcnt(0)
	v_mfma_f32_16x16x32_bf16 v[92:95], v[128:131], v[178:181], v[92:95]
	v_mfma_f32_16x16x32_bf16 v[28:31], v[136:139], v[178:181], v[28:31]
	v_mfma_f32_16x16x32_bf16 v[84:87], v[128:131], v[196:199], v[84:87]
	v_mfma_f32_16x16x32_bf16 v[24:27], v[136:139], v[196:199], v[24:27]
	v_mfma_f32_16x16x32_bf16 v[76:79], v[128:131], v[204:207], v[76:79]
	v_mfma_f32_16x16x32_bf16 v[12:15], v[136:139], v[204:207], v[12:15]
	v_mfma_f32_16x16x32_bf16 v[72:75], v[128:131], v[212:215], v[72:75]
	v_mfma_f32_16x16x32_bf16 v[8:11], v[136:139], v[212:215], v[8:11]
	v_mfma_f32_16x16x32_bf16 v[92:95], v[132:135], v[192:195], v[92:95]
	v_mfma_f32_16x16x32_bf16 v[28:31], v[140:143], v[192:195], v[28:31]
	v_mfma_f32_16x16x32_bf16 v[84:87], v[132:135], v[200:203], v[84:87]
	v_mfma_f32_16x16x32_bf16 v[24:27], v[140:143], v[200:203], v[24:27]
	v_mfma_f32_16x16x32_bf16 v[76:79], v[132:135], v[208:211], v[76:79]
	v_mfma_f32_16x16x32_bf16 v[12:15], v[140:143], v[208:211], v[12:15]
	v_mfma_f32_16x16x32_bf16 v[72:75], v[132:135], v[216:219], v[72:75]
	v_mfma_f32_16x16x32_bf16 v[8:11], v[140:143], v[216:219], v[8:11]
	v_mfma_f32_16x16x32_bf16 v[88:91], v[144:147], v[178:181], v[88:91]
	v_mfma_f32_16x16x32_bf16 v[20:23], v[152:155], v[178:181], v[20:23]
	v_mfma_f32_16x16x32_bf16 v[80:83], v[144:147], v[196:199], v[80:83]
	v_mfma_f32_16x16x32_bf16 v[16:19], v[152:155], v[196:199], v[16:19]
	v_mfma_f32_16x16x32_bf16 v[68:71], v[144:147], v[204:207], v[68:71]
	v_mfma_f32_16x16x32_bf16 v[4:7], v[152:155], v[204:207], v[4:7]
	v_mfma_f32_16x16x32_bf16 v[64:67], v[144:147], v[212:215], v[64:67]
	v_mfma_f32_16x16x32_bf16 v[0:3], v[152:155], v[212:215], v[0:3]
	v_mfma_f32_16x16x32_bf16 v[88:91], v[148:151], v[192:195], v[88:91]
	v_mfma_f32_16x16x32_bf16 v[20:23], v[156:159], v[192:195], v[20:23]
	v_mfma_f32_16x16x32_bf16 v[80:83], v[148:151], v[200:203], v[80:83]
	v_mfma_f32_16x16x32_bf16 v[16:19], v[156:159], v[200:203], v[16:19]
	v_mfma_f32_16x16x32_bf16 v[68:71], v[148:151], v[208:211], v[68:71]
	v_mfma_f32_16x16x32_bf16 v[4:7], v[156:159], v[208:211], v[4:7]
	v_mfma_f32_16x16x32_bf16 v[64:67], v[148:151], v[216:219], v[64:67]
	v_mfma_f32_16x16x32_bf16 v[0:3], v[156:159], v[216:219], v[0:3]
	s_barrier
	s_add_i32 s96, s96, 2
	s_add_u32 s35, s35, 0x100
	s_addc_u32 s49, s49, 0
	s_cmp_gt_u32 s96, 61
	s_mov_b64 s[50:51], s[52:53]
	s_cbranch_scc0 .LBB0_914
	s_lshl_b32 s34, s46, 2
	v_lshl_or_b32 v178, s48, 7, v186
	s_add_i32 s34, s34, s65
	v_ashrrev_i32_e32 v179, 31, v178
	s_mul_hi_i32 s35, s34, 0x30000
	s_mul_i32 s39, s34, 0x30000
	s_and_saveexec_b64 s[48:49], s[0:1]
	s_cbranch_execz .LBB0_917
	s_add_u32 s50, s79, s39
	s_addc_u32 s51, s81, s35
	v_lshl_add_u64 v[132:133], v[178:179], 1, s[50:51]
	v_add_co_u32_e32 v134, vcc, s78, v132
	s_nop 2
	v_cvt_pk_bf16_f32 v128, v124, v125
	s_nop 2
	v_cvt_pk_bf16_f32 v129, v126, v127
	s_nop 2
	v_cvt_pk_bf16_f32 v130, v60, v61
	s_nop 2
	v_cvt_pk_bf16_f32 v131, v62, v63
	s_nop 1
	v_addc_co_u32_e32 v135, vcc, 0, v133, vcc
	s_mov_b32 s17, 0xc000
	global_store_dwordx4 v[132:133], v[128:131], off
	s_nop 1
	s_nop 2
	v_cvt_pk_bf16_f32 v128, v120, v121
	s_nop 2
	v_cvt_pk_bf16_f32 v129, v122, v123
	s_nop 2
	v_cvt_pk_bf16_f32 v130, v52, v53
	s_nop 2
	v_cvt_pk_bf16_f32 v131, v54, v55
	global_store_dwordx4 v[134:135], v[128:131], off
	v_add_co_u32_e32 v134, vcc, s17, v132
	s_nop 0
	s_nop 2
	v_cvt_pk_bf16_f32 v128, v116, v117
	s_nop 2
	v_cvt_pk_bf16_f32 v129, v118, v119
	s_nop 2
	v_cvt_pk_bf16_f32 v130, v56, v57
	s_nop 2
	v_cvt_pk_bf16_f32 v131, v58, v59
	s_nop 0
	v_addc_co_u32_e32 v135, vcc, 0, v133, vcc
	v_add_co_u32_e32 v132, vcc, 0x12000, v132
	global_store_dwordx4 v[134:135], v[128:131], off
	s_nop 0
	v_addc_co_u32_e32 v133, vcc, 0, v133, vcc
	s_nop 2
	v_cvt_pk_bf16_f32 v128, v112, v113
	s_nop 2
	v_cvt_pk_bf16_f32 v129, v114, v115
	s_nop 2
	v_cvt_pk_bf16_f32 v130, v48, v49
	s_nop 2
	v_cvt_pk_bf16_f32 v131, v50, v51
	global_store_dwordx4 v[132:133], v[128:131], off

.LBB0_1077:
	ds_read_b128 v[144:147], v153
	ds_read_b128 v[156:159], v153 offset:1024
	ds_read_b128 v[160:163], v153 offset:2048
	ds_read_b128 v[164:167], v153 offset:3072
	ds_read_b128 v[168:171], v154
	ds_read_b128 v[172:175], v154 offset:1024
	ds_read_b128 v[176:179], v154 offset:2048
	ds_read_b128 v[180:183], v154 offset:3072
	s_add_u32 s28, s26, 0x100
	s_addc_u32 s29, s27, 0
	s_cmpk_eq_i32 s53, 0xbc
	s_cselect_b32 s37, s3, s29
	s_cselect_b32 s36, s2, s28
	s_cselect_b32 s31, s25, s35
	s_cselect_b32 s30, s24, s34
	v_lshl_add_u64 v[148:149], s[26:27], 0, v[136:137]
	s_add_i32 m0, s39, 0xc000
	ds_read_b128 v[184:187], v155
	ds_read_b128 v[188:191], v155 offset:1024
	ds_read_b128 v[192:195], v155 offset:2048
	ds_read_b128 v[196:199], v155 offset:3072
	ds_read_b128 v[200:203], v155 offset:4096
	ds_read_b128 v[204:207], v155 offset:5120
	ds_read_b128 v[208:211], v155 offset:6144
	ds_read_b128 v[212:215], v155 offset:7168
	global_load_lds_dwordx4 v[148:149], off
	v_lshl_add_u64 v[148:149], s[26:27], 0, v[138:139]
	s_add_i32 m0, s39, 0xe000
	s_nop 0
	global_load_lds_dwordx4 v[148:149], off
	s_waitcnt vmcnt(8)
	s_waitcnt lgkmcnt(0)
	s_barrier
	s_waitcnt lgkmcnt(0)
	v_mfma_f32_16x16x32_bf16 v[124:127], v[144:147], v[184:187], v[124:127]
	v_mfma_f32_16x16x32_bf16 v[120:123], v[160:163], v[184:187], v[120:123]
	v_mfma_f32_16x16x32_bf16 v[108:111], v[144:147], v[192:195], v[108:111]
	v_mfma_f32_16x16x32_bf16 v[104:107], v[160:163], v[192:195], v[104:107]
	v_mfma_f32_16x16x32_bf16 v[92:95], v[144:147], v[200:203], v[92:95]
	v_mfma_f32_16x16x32_bf16 v[88:91], v[160:163], v[200:203], v[88:91]
	v_mfma_f32_16x16x32_bf16 v[76:79], v[144:147], v[208:211], v[76:79]
	v_mfma_f32_16x16x32_bf16 v[72:75], v[160:163], v[208:211], v[72:75]
	v_mfma_f32_16x16x32_bf16 v[124:127], v[156:159], v[188:191], v[124:127]
	v_mfma_f32_16x16x32_bf16 v[120:123], v[164:167], v[188:191], v[120:123]
	v_mfma_f32_16x16x32_bf16 v[108:111], v[156:159], v[196:199], v[108:111]
	v_mfma_f32_16x16x32_bf16 v[104:107], v[164:167], v[196:199], v[104:107]
	v_mfma_f32_16x16x32_bf16 v[92:95], v[156:159], v[204:207], v[92:95]
	v_mfma_f32_16x16x32_bf16 v[88:91], v[164:167], v[204:207], v[88:91]
	v_mfma_f32_16x16x32_bf16 v[76:79], v[156:159], v[212:215], v[76:79]
	v_mfma_f32_16x16x32_bf16 v[72:75], v[164:167], v[212:215], v[72:75]
	v_mfma_f32_16x16x32_bf16 v[116:119], v[168:171], v[184:187], v[116:119]
	v_mfma_f32_16x16x32_bf16 v[112:115], v[176:179], v[184:187], v[112:115]
	v_mfma_f32_16x16x32_bf16 v[100:103], v[168:171], v[192:195], v[100:103]
	v_mfma_f32_16x16x32_bf16 v[96:99], v[176:179], v[192:195], v[96:99]
	v_mfma_f32_16x16x32_bf16 v[84:87], v[168:171], v[200:203], v[84:87]
	v_mfma_f32_16x16x32_bf16 v[80:83], v[176:179], v[200:203], v[80:83]
	v_mfma_f32_16x16x32_bf16 v[68:71], v[168:171], v[208:211], v[68:71]
	v_mfma_f32_16x16x32_bf16 v[64:67], v[176:179], v[208:211], v[64:67]
	v_mfma_f32_16x16x32_bf16 v[116:119], v[172:175], v[188:191], v[116:119]
	v_mfma_f32_16x16x32_bf16 v[112:115], v[180:183], v[188:191], v[112:115]
	v_mfma_f32_16x16x32_bf16 v[100:103], v[172:175], v[196:199], v[100:103]
	v_mfma_f32_16x16x32_bf16 v[96:99], v[180:183], v[196:199], v[96:99]
	v_mfma_f32_16x16x32_bf16 v[84:87], v[172:175], v[204:207], v[84:87]
	v_mfma_f32_16x16x32_bf16 v[80:83], v[180:183], v[204:207], v[80:83]
	v_mfma_f32_16x16x32_bf16 v[68:71], v[172:175], v[212:215], v[68:71]
	v_mfma_f32_16x16x32_bf16 v[64:67], v[180:183], v[212:215], v[64:67]
	s_barrier
	s_add_i32 s26, s47, s38
	v_lshl_add_u64 v[148:149], s[30:31], 0, v[130:131]
	s_mov_b32 m0, s26
	ds_read_b128 v[184:187], v155 offset:16384
	ds_read_b128 v[188:191], v155 offset:17408
	ds_read_b128 v[192:195], v155 offset:18432
	ds_read_b128 v[196:199], v155 offset:19456
	ds_read_b128 v[200:203], v155 offset:20480
	ds_read_b128 v[204:207], v155 offset:21504
	ds_read_b128 v[208:211], v155 offset:22528
	ds_read_b128 v[212:215], v155 offset:23552
	global_load_lds_dwordx4 v[148:149], off
	s_add_i32 m0, s26, 0x2000
	s_add_u32 s26, s30, 0x300000
	v_lshl_add_u64 v[216:217], s[30:31], 0, v[134:135]
	s_addc_u32 s27, s31, 0
	s_add_i32 s54, s48, s38
	global_load_lds_dwordx4 v[216:217], off
	v_lshl_add_u64 v[218:219], s[26:27], 0, v[130:131]
	s_mov_b32 m0, s54
	v_lshl_add_u64 v[220:221], s[36:37], 0, v[132:133]
	global_load_lds_dwordx4 v[218:219], off
	v_lshl_add_u64 v[218:219], s[26:27], 0, v[134:135]
	s_add_i32 m0, s54, 0x2000
	s_nop 0
	global_load_lds_dwordx4 v[218:219], off
	v_lshl_add_u64 v[218:219], s[36:37], 0, v[128:129]
	s_mov_b32 m0, s39
	s_nop 0
	global_load_lds_dwordx4 v[218:219], off
	s_mov_b32 m0, s40
	s_nop 0
	global_load_lds_dwordx4 v[220:221], off
	s_waitcnt vmcnt(8)
	s_waitcnt lgkmcnt(0)
	s_barrier
	s_waitcnt lgkmcnt(0)
	v_mfma_f32_16x16x32_bf16 v[60:63], v[144:147], v[184:187], v[60:63]
	v_mfma_f32_16x16x32_bf16 v[56:59], v[160:163], v[184:187], v[56:59]
	v_mfma_f32_16x16x32_bf16 v[44:47], v[144:147], v[192:195], v[44:47]
	v_mfma_f32_16x16x32_bf16 v[40:43], v[160:163], v[192:195], v[40:43]
	v_mfma_f32_16x16x32_bf16 v[28:31], v[144:147], v[200:203], v[28:31]
	v_mfma_f32_16x16x32_bf16 v[24:27], v[160:163], v[200:203], v[24:27]
	v_mfma_f32_16x16x32_bf16 v[12:15], v[144:147], v[208:211], v[12:15]
	v_mfma_f32_16x16x32_bf16 v[8:11], v[160:163], v[208:211], v[8:11]
	v_mfma_f32_16x16x32_bf16 v[60:63], v[156:159], v[188:191], v[60:63]
	v_mfma_f32_16x16x32_bf16 v[56:59], v[164:167], v[188:191], v[56:59]
	v_mfma_f32_16x16x32_bf16 v[44:47], v[156:159], v[196:199], v[44:47]
	v_mfma_f32_16x16x32_bf16 v[40:43], v[164:167], v[196:199], v[40:43]
	v_mfma_f32_16x16x32_bf16 v[28:31], v[156:159], v[204:207], v[28:31]
	v_mfma_f32_16x16x32_bf16 v[24:27], v[164:167], v[204:207], v[24:27]
	v_mfma_f32_16x16x32_bf16 v[12:15], v[156:159], v[212:215], v[12:15]
	v_mfma_f32_16x16x32_bf16 v[8:11], v[164:167], v[212:215], v[8:11]
	v_mfma_f32_16x16x32_bf16 v[52:55], v[168:171], v[184:187], v[52:55]
	v_mfma_f32_16x16x32_bf16 v[48:51], v[176:179], v[184:187], v[48:51]
	v_mfma_f32_16x16x32_bf16 v[36:39], v[168:171], v[192:195], v[36:39]
	v_mfma_f32_16x16x32_bf16 v[32:35], v[176:179], v[192:195], v[32:35]
	v_mfma_f32_16x16x32_bf16 v[20:23], v[168:171], v[200:203], v[20:23]
	v_mfma_f32_16x16x32_bf16 v[16:19], v[176:179], v[200:203], v[16:19]
	v_mfma_f32_16x16x32_bf16 v[4:7], v[168:171], v[208:211], v[4:7]
	v_mfma_f32_16x16x32_bf16 v[0:3], v[176:179], v[208:211], v[0:3]
	v_mfma_f32_16x16x32_bf16 v[52:55], v[172:175], v[188:191], v[52:55]
	v_mfma_f32_16x16x32_bf16 v[48:51], v[180:183], v[188:191], v[48:51]
	v_mfma_f32_16x16x32_bf16 v[36:39], v[172:175], v[196:199], v[36:39]
	v_mfma_f32_16x16x32_bf16 v[32:35], v[180:183], v[196:199], v[32:35]
	v_mfma_f32_16x16x32_bf16 v[20:23], v[172:175], v[204:207], v[20:23]
	v_mfma_f32_16x16x32_bf16 v[16:19], v[180:183], v[204:207], v[16:19]
	v_mfma_f32_16x16x32_bf16 v[4:7], v[172:175], v[212:215], v[4:7]
	v_mfma_f32_16x16x32_bf16 v[0:3], v[180:183], v[212:215], v[0:3]
	s_barrier
	s_add_i32 s54, 0, 0x18000
	s_add_i32 s55, 0, 0x1c000
	v_add_u32_e32 v164, s54, v151
	v_add_u32_e32 v180, s55, v151
	ds_read_b128 v[144:147], v164
	ds_read_b128 v[156:159], v164 offset:1024
	ds_read_b128 v[160:163], v164 offset:2048
	ds_read_b128 v[164:167], v164 offset:3072
	ds_read_b128 v[168:171], v180
	ds_read_b128 v[172:175], v180 offset:1024
	ds_read_b128 v[176:179], v180 offset:2048
	ds_read_b128 v[180:183], v180 offset:3072
	s_add_u32 s26, s36, 0x300000
	s_addc_u32 s27, s37, 0
	s_mov_b32 m0, s41
	v_lshl_add_u64 v[222:223], s[26:27], 0, v[128:129]
	ds_read_b128 v[184:187], v155 offset:32768
	ds_read_b128 v[188:191], v155 offset:33792
	ds_read_b128 v[192:195], v155 offset:34816
	ds_read_b128 v[196:199], v155 offset:35840
	ds_read_b128 v[200:203], v155 offset:36864
	ds_read_b128 v[204:207], v155 offset:37888
	ds_read_b128 v[208:211], v155 offset:38912
	ds_read_b128 v[212:215], v155 offset:39936
	global_load_lds_dwordx4 v[222:223], off
	v_lshl_add_u64 v[222:223], s[26:27], 0, v[132:133]
	s_mov_b32 m0, s42
	s_nop 0
	global_load_lds_dwordx4 v[222:223], off
	s_waitcnt vmcnt(8)
	s_waitcnt lgkmcnt(0)
	s_barrier
	s_waitcnt lgkmcnt(0)
	v_mfma_f32_16x16x32_bf16 v[124:127], v[144:147], v[184:187], v[124:127]
	v_mfma_f32_16x16x32_bf16 v[120:123], v[160:163], v[184:187], v[120:123]
	v_mfma_f32_16x16x32_bf16 v[108:111], v[144:147], v[192:195], v[108:111]
	v_mfma_f32_16x16x32_bf16 v[104:107], v[160:163], v[192:195], v[104:107]
	v_mfma_f32_16x16x32_bf16 v[92:95], v[144:147], v[200:203], v[92:95]
	v_mfma_f32_16x16x32_bf16 v[88:91], v[160:163], v[200:203], v[88:91]
	v_mfma_f32_16x16x32_bf16 v[76:79], v[144:147], v[208:211], v[76:79]
	v_mfma_f32_16x16x32_bf16 v[72:75], v[160:163], v[208:211], v[72:75]
	v_mfma_f32_16x16x32_bf16 v[124:127], v[156:159], v[188:191], v[124:127]
	v_mfma_f32_16x16x32_bf16 v[120:123], v[164:167], v[188:191], v[120:123]
	v_mfma_f32_16x16x32_bf16 v[108:111], v[156:159], v[196:199], v[108:111]
	v_mfma_f32_16x16x32_bf16 v[104:107], v[164:167], v[196:199], v[104:107]
	v_mfma_f32_16x16x32_bf16 v[92:95], v[156:159], v[204:207], v[92:95]
	v_mfma_f32_16x16x32_bf16 v[88:91], v[164:167], v[204:207], v[88:91]
	v_mfma_f32_16x16x32_bf16 v[76:79], v[156:159], v[212:215], v[76:79]
	v_mfma_f32_16x16x32_bf16 v[72:75], v[164:167], v[212:215], v[72:75]
	v_mfma_f32_16x16x32_bf16 v[116:119], v[168:171], v[184:187], v[116:119]
	v_mfma_f32_16x16x32_bf16 v[112:115], v[176:179], v[184:187], v[112:115]
	v_mfma_f32_16x16x32_bf16 v[100:103], v[168:171], v[192:195], v[100:103]
	v_mfma_f32_16x16x32_bf16 v[96:99], v[176:179], v[192:195], v[96:99]
	v_mfma_f32_16x16x32_bf16 v[84:87], v[168:171], v[200:203], v[84:87]
	v_mfma_f32_16x16x32_bf16 v[80:83], v[176:179], v[200:203], v[80:83]
	v_mfma_f32_16x16x32_bf16 v[68:71], v[168:171], v[208:211], v[68:71]
	v_mfma_f32_16x16x32_bf16 v[64:67], v[176:179], v[208:211], v[64:67]
	v_mfma_f32_16x16x32_bf16 v[116:119], v[172:175], v[188:191], v[116:119]
	v_mfma_f32_16x16x32_bf16 v[112:115], v[180:183], v[188:191], v[112:115]
	v_mfma_f32_16x16x32_bf16 v[100:103], v[172:175], v[196:199], v[100:103]
	v_mfma_f32_16x16x32_bf16 v[96:99], v[180:183], v[196:199], v[96:99]
	v_mfma_f32_16x16x32_bf16 v[84:87], v[172:175], v[204:207], v[84:87]
	v_mfma_f32_16x16x32_bf16 v[80:83], v[180:183], v[204:207], v[80:83]
	v_mfma_f32_16x16x32_bf16 v[68:71], v[172:175], v[212:215], v[68:71]
	v_mfma_f32_16x16x32_bf16 v[64:67], v[180:183], v[212:215], v[64:67]
	s_barrier
	s_add_i32 s26, s54, s38
	v_lshl_add_u64 v[148:149], v[148:149], 0, s[10:11]
	s_mov_b32 m0, s26
	ds_read_b128 v[184:187], v155 offset:49152
	ds_read_b128 v[188:191], v155 offset:50176
	ds_read_b128 v[192:195], v155 offset:51200
	ds_read_b128 v[196:199], v155 offset:52224
	ds_read_b128 v[200:203], v155 offset:53248
	ds_read_b128 v[204:207], v155 offset:54272
	ds_read_b128 v[208:211], v155 offset:55296
	ds_read_b128 v[212:215], v155 offset:56320
	global_load_lds_dwordx4 v[148:149], off
	s_add_i32 m0, s26, 0x2000
	s_add_u32 s26, s30, 0x300080
	v_lshl_add_u64 v[148:149], v[216:217], 0, s[10:11]
	s_addc_u32 s27, s31, 0
	s_add_i32 s30, s55, s38
	global_load_lds_dwordx4 v[148:149], off
	v_lshl_add_u64 v[148:149], s[26:27], 0, v[130:131]
	s_mov_b32 m0, s30
	s_nop 0
	global_load_lds_dwordx4 v[148:149], off
	v_lshl_add_u64 v[148:149], s[26:27], 0, v[134:135]
	s_add_i32 m0, s30, 0x2000
	s_nop 0
	global_load_lds_dwordx4 v[148:149], off
	v_lshl_add_u64 v[148:149], v[218:219], 0, s[10:11]
	s_mov_b32 m0, s44
	s_nop 0
	global_load_lds_dwordx4 v[148:149], off
	v_lshl_add_u64 v[148:149], v[220:221], 0, s[10:11]
	s_mov_b32 m0, s45
	s_nop 0
	global_load_lds_dwordx4 v[148:149], off
	s_waitcnt vmcnt(8)
	s_waitcnt lgkmcnt(0)
	s_barrier
	s_waitcnt lgkmcnt(0)
	v_mfma_f32_16x16x32_bf16 v[60:63], v[144:147], v[184:187], v[60:63]
	v_mfma_f32_16x16x32_bf16 v[56:59], v[160:163], v[184:187], v[56:59]
	v_mfma_f32_16x16x32_bf16 v[44:47], v[144:147], v[192:195], v[44:47]
	v_mfma_f32_16x16x32_bf16 v[40:43], v[160:163], v[192:195], v[40:43]
	v_mfma_f32_16x16x32_bf16 v[28:31], v[144:147], v[200:203], v[28:31]
	v_mfma_f32_16x16x32_bf16 v[24:27], v[160:163], v[200:203], v[24:27]
	v_mfma_f32_16x16x32_bf16 v[12:15], v[144:147], v[208:211], v[12:15]
	v_mfma_f32_16x16x32_bf16 v[8:11], v[160:163], v[208:211], v[8:11]
	v_mfma_f32_16x16x32_bf16 v[60:63], v[156:159], v[188:191], v[60:63]
	v_mfma_f32_16x16x32_bf16 v[56:59], v[164:167], v[188:191], v[56:59]
	v_mfma_f32_16x16x32_bf16 v[44:47], v[156:159], v[196:199], v[44:47]
	v_mfma_f32_16x16x32_bf16 v[40:43], v[164:167], v[196:199], v[40:43]
	v_mfma_f32_16x16x32_bf16 v[28:31], v[156:159], v[204:207], v[28:31]
	v_mfma_f32_16x16x32_bf16 v[24:27], v[164:167], v[204:207], v[24:27]
	v_mfma_f32_16x16x32_bf16 v[12:15], v[156:159], v[212:215], v[12:15]
	v_mfma_f32_16x16x32_bf16 v[8:11], v[164:167], v[212:215], v[8:11]
	v_mfma_f32_16x16x32_bf16 v[52:55], v[168:171], v[184:187], v[52:55]
	v_mfma_f32_16x16x32_bf16 v[48:51], v[176:179], v[184:187], v[48:51]
	v_mfma_f32_16x16x32_bf16 v[36:39], v[168:171], v[192:195], v[36:39]
	v_mfma_f32_16x16x32_bf16 v[32:35], v[176:179], v[192:195], v[32:35]
	v_mfma_f32_16x16x32_bf16 v[20:23], v[168:171], v[200:203], v[20:23]
	v_mfma_f32_16x16x32_bf16 v[16:19], v[176:179], v[200:203], v[16:19]
	v_mfma_f32_16x16x32_bf16 v[4:7], v[168:171], v[208:211], v[4:7]
	v_mfma_f32_16x16x32_bf16 v[0:3], v[176:179], v[208:211], v[0:3]
	v_mfma_f32_16x16x32_bf16 v[52:55], v[172:175], v[188:191], v[52:55]
	v_mfma_f32_16x16x32_bf16 v[48:51], v[180:183], v[188:191], v[48:51]
	v_mfma_f32_16x16x32_bf16 v[36:39], v[172:175], v[196:199], v[36:39]
	v_mfma_f32_16x16x32_bf16 v[32:35], v[180:183], v[196:199], v[32:35]
	v_mfma_f32_16x16x32_bf16 v[20:23], v[172:175], v[204:207], v[20:23]
	v_mfma_f32_16x16x32_bf16 v[16:19], v[180:183], v[204:207], v[16:19]
	v_mfma_f32_16x16x32_bf16 v[4:7], v[172:175], v[212:215], v[4:7]
	v_mfma_f32_16x16x32_bf16 v[0:3], v[180:183], v[212:215], v[0:3]
	s_barrier
	s_add_i32 s53, s53, 2
	s_add_u32 s34, s34, 0x100
	s_addc_u32 s35, s35, 0
	s_cmpk_gt_u32 s53, 0xbd
	s_mov_b64 s[26:27], s[28:29]
	s_cbranch_scc0 .LBB0_1077
	s_and_b64 vcc, exec, s[12:13]
	s_cbranch_vccz .LBB0_1080
	s_barrier

.LBB0_1313:
	ds_read_b128 v[48:51], v163
	ds_read_b128 v[52:55], v163 offset:1024
	ds_read_b128 v[152:155], v163 offset:2048
	ds_read_b128 v[156:159], v163 offset:3072
	ds_read_b128 v[168:171], v164
	ds_read_b128 v[172:175], v164 offset:1024
	ds_read_b128 v[176:179], v164 offset:2048
	ds_read_b128 v[180:183], v164 offset:3072
	s_add_u32 s42, s40, 0xfff00080
	s_addc_u32 s43, s41, -1
	s_cmp_eq_u32 s60, 60
	s_cselect_b32 s45, s14, s43
	s_cselect_b32 s44, s29, s42
	s_cselect_b32 s43, s27, s35
	s_cselect_b32 s42, s39, s34
	v_lshl_add_u64 v[216:217], s[40:41], 0, v[144:145]
	s_add_i32 m0, s47, 0xc000
	ds_read_b128 v[184:187], v165
	ds_read_b128 v[188:191], v165 offset:1024
	ds_read_b128 v[192:195], v165 offset:2048
	ds_read_b128 v[196:199], v165 offset:3072
	ds_read_b128 v[200:203], v165 offset:4096
	ds_read_b128 v[204:207], v165 offset:5120
	ds_read_b128 v[208:211], v165 offset:6144
	ds_read_b128 v[212:215], v165 offset:7168
	global_load_lds_dwordx4 v[216:217], off
	v_lshl_add_u64 v[216:217], s[40:41], 0, v[146:147]
	s_add_i32 m0, s47, 0xe000
	s_nop 0
	global_load_lds_dwordx4 v[216:217], off
	s_waitcnt vmcnt(8)
	s_waitcnt lgkmcnt(0)
	s_barrier
	s_waitcnt lgkmcnt(0)
	v_mfma_f32_16x16x32_bf16 v[44:47], v[48:51], v[184:187], v[44:47]
	v_mfma_f32_16x16x32_bf16 v[40:43], v[152:155], v[184:187], v[40:43]
	v_mfma_f32_16x16x32_bf16 v[124:127], v[48:51], v[192:195], v[124:127]
	v_mfma_f32_16x16x32_bf16 v[120:123], v[152:155], v[192:195], v[120:123]
	v_mfma_f32_16x16x32_bf16 v[108:111], v[48:51], v[200:203], v[108:111]
	v_mfma_f32_16x16x32_bf16 v[104:107], v[152:155], v[200:203], v[104:107]
	v_mfma_f32_16x16x32_bf16 v[92:95], v[48:51], v[208:211], v[92:95]
	v_mfma_f32_16x16x32_bf16 v[88:91], v[152:155], v[208:211], v[88:91]
	v_mfma_f32_16x16x32_bf16 v[44:47], v[52:55], v[188:191], v[44:47]
	v_mfma_f32_16x16x32_bf16 v[40:43], v[156:159], v[188:191], v[40:43]
	v_mfma_f32_16x16x32_bf16 v[124:127], v[52:55], v[196:199], v[124:127]
	v_mfma_f32_16x16x32_bf16 v[120:123], v[156:159], v[196:199], v[120:123]
	v_mfma_f32_16x16x32_bf16 v[108:111], v[52:55], v[204:207], v[108:111]
	v_mfma_f32_16x16x32_bf16 v[104:107], v[156:159], v[204:207], v[104:107]
	v_mfma_f32_16x16x32_bf16 v[92:95], v[52:55], v[212:215], v[92:95]
	v_mfma_f32_16x16x32_bf16 v[88:91], v[156:159], v[212:215], v[88:91]
	v_mfma_f32_16x16x32_bf16 v[132:135], v[168:171], v[184:187], v[132:135]
	v_mfma_f32_16x16x32_bf16 v[128:131], v[176:179], v[184:187], v[128:131]
	v_mfma_f32_16x16x32_bf16 v[116:119], v[168:171], v[192:195], v[116:119]
	v_mfma_f32_16x16x32_bf16 v[112:115], v[176:179], v[192:195], v[112:115]
	v_mfma_f32_16x16x32_bf16 v[100:103], v[168:171], v[200:203], v[100:103]
	v_mfma_f32_16x16x32_bf16 v[96:99], v[176:179], v[200:203], v[96:99]
	v_mfma_f32_16x16x32_bf16 v[84:87], v[168:171], v[208:211], v[84:87]
	v_mfma_f32_16x16x32_bf16 v[80:83], v[176:179], v[208:211], v[80:83]
	v_mfma_f32_16x16x32_bf16 v[132:135], v[172:175], v[188:191], v[132:135]
	v_mfma_f32_16x16x32_bf16 v[128:131], v[180:183], v[188:191], v[128:131]
	v_mfma_f32_16x16x32_bf16 v[116:119], v[172:175], v[196:199], v[116:119]
	v_mfma_f32_16x16x32_bf16 v[112:115], v[180:183], v[196:199], v[112:115]
	v_mfma_f32_16x16x32_bf16 v[100:103], v[172:175], v[204:207], v[100:103]
	v_mfma_f32_16x16x32_bf16 v[96:99], v[180:183], v[204:207], v[96:99]
	v_mfma_f32_16x16x32_bf16 v[84:87], v[172:175], v[212:215], v[84:87]
	v_mfma_f32_16x16x32_bf16 v[80:83], v[180:183], v[212:215], v[80:83]
	s_barrier
	s_add_i32 s61, s56, s46
	v_lshl_add_u64 v[216:217], s[42:43], 0, v[138:139]
	s_mov_b32 m0, s61
	ds_read_b128 v[184:187], v165 offset:16384
	ds_read_b128 v[188:191], v165 offset:17408
	ds_read_b128 v[192:195], v165 offset:18432
	ds_read_b128 v[196:199], v165 offset:19456
	ds_read_b128 v[200:203], v165 offset:20480
	ds_read_b128 v[204:207], v165 offset:21504
	ds_read_b128 v[208:211], v165 offset:22528
	ds_read_b128 v[212:215], v165 offset:23552
	global_load_lds_dwordx4 v[216:217], off
	s_add_i32 m0, s61, 0x2000
	s_add_u32 s62, s42, 0x100000
	v_lshl_add_u64 v[218:219], s[42:43], 0, v[142:143]
	s_addc_u32 s63, s43, 0
	s_add_i32 s61, s57, s46
	global_load_lds_dwordx4 v[218:219], off
	v_lshl_add_u64 v[220:221], s[62:63], 0, v[138:139]
	s_mov_b32 m0, s61
	v_lshl_add_u64 v[222:223], s[44:45], 0, v[140:141]
	global_load_lds_dwordx4 v[220:221], off
	v_lshl_add_u64 v[220:221], s[62:63], 0, v[142:143]
	s_add_i32 m0, s61, 0x2000
	s_nop 0
	global_load_lds_dwordx4 v[220:221], off
	v_lshl_add_u64 v[220:221], s[44:45], 0, v[136:137]
	s_mov_b32 m0, s47
	s_nop 0
	global_load_lds_dwordx4 v[220:221], off
	s_mov_b32 m0, s48
	s_nop 0
	global_load_lds_dwordx4 v[222:223], off
	s_waitcnt vmcnt(8)
	s_waitcnt lgkmcnt(0)
	s_barrier
	s_waitcnt lgkmcnt(0)
	v_mfma_f32_16x16x32_bf16 v[76:79], v[48:51], v[184:187], v[76:79]
	v_mfma_f32_16x16x32_bf16 v[72:75], v[152:155], v[184:187], v[72:75]
	v_mfma_f32_16x16x32_bf16 v[60:63], v[48:51], v[192:195], v[60:63]
	v_mfma_f32_16x16x32_bf16 v[56:59], v[152:155], v[192:195], v[56:59]
	v_mfma_f32_16x16x32_bf16 v[28:31], v[48:51], v[200:203], v[28:31]
	v_mfma_f32_16x16x32_bf16 v[24:27], v[152:155], v[200:203], v[24:27]
	v_mfma_f32_16x16x32_bf16 v[12:15], v[48:51], v[208:211], v[12:15]
	v_mfma_f32_16x16x32_bf16 v[8:11], v[152:155], v[208:211], v[8:11]
	v_mfma_f32_16x16x32_bf16 v[76:79], v[52:55], v[188:191], v[76:79]
	v_mfma_f32_16x16x32_bf16 v[72:75], v[156:159], v[188:191], v[72:75]
	v_mfma_f32_16x16x32_bf16 v[60:63], v[52:55], v[196:199], v[60:63]
	v_mfma_f32_16x16x32_bf16 v[56:59], v[156:159], v[196:199], v[56:59]
	v_mfma_f32_16x16x32_bf16 v[28:31], v[52:55], v[204:207], v[28:31]
	v_mfma_f32_16x16x32_bf16 v[24:27], v[156:159], v[204:207], v[24:27]
	v_mfma_f32_16x16x32_bf16 v[12:15], v[52:55], v[212:215], v[12:15]
	v_mfma_f32_16x16x32_bf16 v[8:11], v[156:159], v[212:215], v[8:11]
	v_mfma_f32_16x16x32_bf16 v[36:39], v[168:171], v[192:195], v[36:39]
	v_mfma_f32_16x16x32_bf16 v[32:35], v[176:179], v[192:195], v[32:35]
	v_mfma_f32_16x16x32_bf16 v[20:23], v[168:171], v[200:203], v[20:23]
	v_mfma_f32_16x16x32_bf16 v[16:19], v[176:179], v[200:203], v[16:19]
	v_mfma_f32_16x16x32_bf16 v[4:7], v[168:171], v[208:211], v[4:7]
	v_mfma_f32_16x16x32_bf16 v[0:3], v[176:179], v[208:211], v[0:3]
	v_mfma_f32_16x16x32_bf16 v[48:51], v[168:171], v[184:187], v[68:71]
	v_mfma_f32_16x16x32_bf16 v[52:55], v[176:179], v[184:187], v[64:67]
	v_mfma_f32_16x16x32_bf16 v[36:39], v[172:175], v[196:199], v[36:39]
	v_mfma_f32_16x16x32_bf16 v[32:35], v[180:183], v[196:199], v[32:35]
	v_mfma_f32_16x16x32_bf16 v[20:23], v[172:175], v[204:207], v[20:23]
	v_mfma_f32_16x16x32_bf16 v[16:19], v[180:183], v[204:207], v[16:19]
	v_mfma_f32_16x16x32_bf16 v[4:7], v[172:175], v[212:215], v[4:7]
	v_mfma_f32_16x16x32_bf16 v[0:3], v[180:183], v[212:215], v[0:3]
	v_mfma_f32_16x16x32_bf16 v[48:51], v[172:175], v[188:191], v[48:51]
	v_mfma_f32_16x16x32_bf16 v[52:55], v[180:183], v[188:191], v[52:55]
	s_barrier
	s_add_i32 s61, 0, 0x18000
	s_add_i32 s62, 0, 0x1c000
	v_add_u32_e32 v156, s61, v161
	v_add_u32_e32 v167, s62, v161
	ds_read_b128 v[64:67], v156
	ds_read_b128 v[68:71], v156 offset:1024
	ds_read_b128 v[152:155], v156 offset:2048
	ds_read_b128 v[156:159], v156 offset:3072
	ds_read_b128 v[168:171], v167
	ds_read_b128 v[172:175], v167 offset:1024
	ds_read_b128 v[176:179], v167 offset:2048
	ds_read_b128 v[180:183], v167 offset:3072
	s_add_u32 s44, s44, 0x100000
	s_addc_u32 s45, s45, 0
	s_mov_b32 m0, s49
	v_lshl_add_u64 v[226:227], s[44:45], 0, v[136:137]
	ds_read_b128 v[184:187], v165 offset:32768
	ds_read_b128 v[188:191], v165 offset:33792
	ds_read_b128 v[192:195], v165 offset:34816
	ds_read_b128 v[196:199], v165 offset:35840
	ds_read_b128 v[200:203], v165 offset:36864
	ds_read_b128 v[204:207], v165 offset:37888
	ds_read_b128 v[208:211], v165 offset:38912
	ds_read_b128 v[212:215], v165 offset:39936
	global_load_lds_dwordx4 v[226:227], off
	v_lshl_add_u64 v[226:227], s[44:45], 0, v[140:141]
	s_mov_b32 m0, s50
	s_nop 0
	global_load_lds_dwordx4 v[226:227], off
	s_waitcnt vmcnt(8)
	s_waitcnt lgkmcnt(0)
	s_barrier
	s_waitcnt lgkmcnt(0)
	v_mfma_f32_16x16x32_bf16 v[44:47], v[64:67], v[184:187], v[44:47]
	v_mfma_f32_16x16x32_bf16 v[40:43], v[152:155], v[184:187], v[40:43]
	v_mfma_f32_16x16x32_bf16 v[124:127], v[64:67], v[192:195], v[124:127]
	v_mfma_f32_16x16x32_bf16 v[120:123], v[152:155], v[192:195], v[120:123]
	v_mfma_f32_16x16x32_bf16 v[108:111], v[64:67], v[200:203], v[108:111]
	v_mfma_f32_16x16x32_bf16 v[104:107], v[152:155], v[200:203], v[104:107]
	v_mfma_f32_16x16x32_bf16 v[92:95], v[64:67], v[208:211], v[92:95]
	v_mfma_f32_16x16x32_bf16 v[88:91], v[152:155], v[208:211], v[88:91]
	v_mfma_f32_16x16x32_bf16 v[44:47], v[68:71], v[188:191], v[44:47]
	v_mfma_f32_16x16x32_bf16 v[40:43], v[156:159], v[188:191], v[40:43]
	v_mfma_f32_16x16x32_bf16 v[124:127], v[68:71], v[196:199], v[124:127]
	v_mfma_f32_16x16x32_bf16 v[120:123], v[156:159], v[196:199], v[120:123]
	v_mfma_f32_16x16x32_bf16 v[108:111], v[68:71], v[204:207], v[108:111]
	v_mfma_f32_16x16x32_bf16 v[104:107], v[156:159], v[204:207], v[104:107]
	v_mfma_f32_16x16x32_bf16 v[92:95], v[68:71], v[212:215], v[92:95]
	v_mfma_f32_16x16x32_bf16 v[88:91], v[156:159], v[212:215], v[88:91]
	v_mfma_f32_16x16x32_bf16 v[132:135], v[168:171], v[184:187], v[132:135]
	v_mfma_f32_16x16x32_bf16 v[128:131], v[176:179], v[184:187], v[128:131]
	v_mfma_f32_16x16x32_bf16 v[116:119], v[168:171], v[192:195], v[116:119]
	v_mfma_f32_16x16x32_bf16 v[112:115], v[176:179], v[192:195], v[112:115]
	v_mfma_f32_16x16x32_bf16 v[100:103], v[168:171], v[200:203], v[100:103]
	v_mfma_f32_16x16x32_bf16 v[96:99], v[176:179], v[200:203], v[96:99]
	v_mfma_f32_16x16x32_bf16 v[84:87], v[168:171], v[208:211], v[84:87]
	v_mfma_f32_16x16x32_bf16 v[80:83], v[176:179], v[208:211], v[80:83]
	v_mfma_f32_16x16x32_bf16 v[132:135], v[172:175], v[188:191], v[132:135]
	v_mfma_f32_16x16x32_bf16 v[128:131], v[180:183], v[188:191], v[128:131]
	v_mfma_f32_16x16x32_bf16 v[116:119], v[172:175], v[196:199], v[116:119]
	v_mfma_f32_16x16x32_bf16 v[112:115], v[180:183], v[196:199], v[112:115]
	v_mfma_f32_16x16x32_bf16 v[100:103], v[172:175], v[204:207], v[100:103]
	v_mfma_f32_16x16x32_bf16 v[96:99], v[180:183], v[204:207], v[96:99]
	v_mfma_f32_16x16x32_bf16 v[84:87], v[172:175], v[212:215], v[84:87]
	v_mfma_f32_16x16x32_bf16 v[80:83], v[180:183], v[212:215], v[80:83]
	s_barrier
	s_add_i32 s44, s61, s46
	v_lshl_add_u64 v[216:217], v[216:217], 0, s[22:23]
	s_mov_b32 m0, s44
	ds_read_b128 v[184:187], v165 offset:49152
	ds_read_b128 v[188:191], v165 offset:50176
	ds_read_b128 v[192:195], v165 offset:51200
	ds_read_b128 v[196:199], v165 offset:52224
	ds_read_b128 v[200:203], v165 offset:53248
	ds_read_b128 v[204:207], v165 offset:54272
	ds_read_b128 v[208:211], v165 offset:55296
	ds_read_b128 v[212:215], v165 offset:56320
	global_load_lds_dwordx4 v[216:217], off
	s_add_i32 m0, s44, 0x2000
	s_add_u32 s42, s42, 0x100080
	v_lshl_add_u64 v[216:217], v[218:219], 0, s[22:23]
	s_addc_u32 s43, s43, 0
	s_add_i32 s44, s62, s46
	global_load_lds_dwordx4 v[216:217], off
	v_lshl_add_u64 v[216:217], s[42:43], 0, v[138:139]
	s_mov_b32 m0, s44
	s_nop 0
	global_load_lds_dwordx4 v[216:217], off
	v_lshl_add_u64 v[216:217], s[42:43], 0, v[142:143]
	s_add_i32 m0, s44, 0x2000
	s_nop 0
	global_load_lds_dwordx4 v[216:217], off
	v_lshl_add_u64 v[216:217], v[220:221], 0, s[22:23]
	s_mov_b32 m0, s52
	s_nop 0
	global_load_lds_dwordx4 v[216:217], off
	v_lshl_add_u64 v[216:217], v[222:223], 0, s[22:23]
	s_mov_b32 m0, s53
	s_nop 0
	global_load_lds_dwordx4 v[216:217], off
	s_waitcnt vmcnt(8)
	s_waitcnt lgkmcnt(0)
	s_barrier
	s_waitcnt lgkmcnt(0)
	v_mfma_f32_16x16x32_bf16 v[76:79], v[64:67], v[184:187], v[76:79]
	v_mfma_f32_16x16x32_bf16 v[72:75], v[152:155], v[184:187], v[72:75]
	v_mfma_f32_16x16x32_bf16 v[60:63], v[64:67], v[192:195], v[60:63]
	v_mfma_f32_16x16x32_bf16 v[56:59], v[152:155], v[192:195], v[56:59]
	v_mfma_f32_16x16x32_bf16 v[28:31], v[64:67], v[200:203], v[28:31]
	v_mfma_f32_16x16x32_bf16 v[24:27], v[152:155], v[200:203], v[24:27]
	v_mfma_f32_16x16x32_bf16 v[12:15], v[64:67], v[208:211], v[12:15]
	v_mfma_f32_16x16x32_bf16 v[8:11], v[152:155], v[208:211], v[8:11]
	v_mfma_f32_16x16x32_bf16 v[76:79], v[68:71], v[188:191], v[76:79]
	v_mfma_f32_16x16x32_bf16 v[72:75], v[156:159], v[188:191], v[72:75]
	v_mfma_f32_16x16x32_bf16 v[60:63], v[68:71], v[196:199], v[60:63]
	v_mfma_f32_16x16x32_bf16 v[56:59], v[156:159], v[196:199], v[56:59]
	v_mfma_f32_16x16x32_bf16 v[28:31], v[68:71], v[204:207], v[28:31]
	v_mfma_f32_16x16x32_bf16 v[24:27], v[156:159], v[204:207], v[24:27]
	v_mfma_f32_16x16x32_bf16 v[12:15], v[68:71], v[212:215], v[12:15]
	v_mfma_f32_16x16x32_bf16 v[8:11], v[156:159], v[212:215], v[8:11]
	v_mfma_f32_16x16x32_bf16 v[48:51], v[168:171], v[184:187], v[48:51]
	v_mfma_f32_16x16x32_bf16 v[68:71], v[172:175], v[188:191], v[48:51]
	v_mfma_f32_16x16x32_bf16 v[48:51], v[176:179], v[184:187], v[52:55]
	v_mfma_f32_16x16x32_bf16 v[36:39], v[168:171], v[192:195], v[36:39]
	v_mfma_f32_16x16x32_bf16 v[32:35], v[176:179], v[192:195], v[32:35]
	v_mfma_f32_16x16x32_bf16 v[20:23], v[168:171], v[200:203], v[20:23]
	v_mfma_f32_16x16x32_bf16 v[16:19], v[176:179], v[200:203], v[16:19]
	v_mfma_f32_16x16x32_bf16 v[4:7], v[168:171], v[208:211], v[4:7]
	v_mfma_f32_16x16x32_bf16 v[0:3], v[176:179], v[208:211], v[0:3]
	v_mfma_f32_16x16x32_bf16 v[64:67], v[180:183], v[188:191], v[48:51]
	v_mfma_f32_16x16x32_bf16 v[36:39], v[172:175], v[196:199], v[36:39]
	v_mfma_f32_16x16x32_bf16 v[32:35], v[180:183], v[196:199], v[32:35]
	v_mfma_f32_16x16x32_bf16 v[20:23], v[172:175], v[204:207], v[20:23]
	v_mfma_f32_16x16x32_bf16 v[16:19], v[180:183], v[204:207], v[16:19]
	v_mfma_f32_16x16x32_bf16 v[4:7], v[172:175], v[212:215], v[4:7]
	v_mfma_f32_16x16x32_bf16 v[0:3], v[180:183], v[212:215], v[0:3]
	s_barrier
	s_add_i32 s60, s60, 2
	s_add_u32 s40, s40, 0x100
	s_addc_u32 s41, s41, 0
	s_add_u32 s34, s34, 0x100
	s_addc_u32 s35, s35, 0
	s_cmp_gt_u32 s60, 61
	s_cbranch_scc0 .LBB0_1313
	s_and_b64 vcc, exec, s[24:25]
	s_cbranch_vccz .LBB0_1316
	s_barrier
